# mla_fin: norm weights staged once per wave into LDS and read with ds_read_b128 instead of flat loads serialized behind stores
# speedup vs baseline: 1.0085x; 1.0083x over previous
; DI int lane_asm() { int l_; asm volatile("v_mbcnt_lo_u32_b32 %0, -1, 0\n\tv_mbcnt_hi_u32_b32 %0, -1, %0" : "=v"(l_)); return l_; }
; DI void phase_mla_fin(ArgsP a, int tb_, int l, char* shm, int vcu, int G) {
;     int tid_ = tb_ + lane_asm(); asm volatile("" : "+v"(tid_)); const int tid = tid_, lane = tid & 63, wave = tid >> 6;
;     const int gw = vcu * NWAVES + wave, NGW = G * NWAVES;
;     const bf16_t* zcq = (const bf16_t*)(a->ws + A_ZCQ); const bf16_t* zkv = (const bf16_t*)(a->ws + A_ZKV);
;     const bf16_t* qraw = (const bf16_t*)(a->ws + A_QRAW); const bf16_t* kvraw = (const bf16_t*)(a->ws + A_KVRAW);
;     bf16_t* Qb = (bf16_t*)(a->ws + A_Q); bf16_t* Kb = (bf16_t*)(a->ws + A_K); bf16_t* Vt = (bf16_t*)(a->ws + A_VT);
;     const float* gqn0 = a->in[I_GQN] + l * 96; const float* gkn0 = a->in[I_GKN] + l * 96;
;     ...
;     for (int it = gw; it < (M / 8) * 2; it += NGW) {
;         const int m = (it >> 1) * 8 + (lane >> 3), h = lane & 7;
;         const bool lat = m < ML; const int t = lat ? (m & 4095) : ((m - ML) & 255); const int b = lat ? (m >> 12) : ((m - ML) >> 8); const int pos = lat ? LC + t : t;
;         const size_t bh = (size_t)(b * 8 + h);
;         const f32x4* rp = (const f32x4*)((const float*)(a->ws + WS_ROPE) + (size_t)(lat ? t : 0) * 32);
;         f32x4 rc[4], rs[4];
; #pragma unroll
;         for (int i = 0; i < 4; ++i) { rc[i] = rp[i]; rs[i] = rp[4 + i]; }
;         if (!(it & 1)) {
.LBB0_962:
	s_mov_b64 s[6:7], s[64:65]
	v_mbcnt_lo_u32_b32 v0, -1, 0
	v_mbcnt_hi_u32_b32 v0, -1, v0
	s_movk_i32 s0, 0x2200
	v_add_u32_e32 v1, s1, v0
	s_nop 0
	v_ashrrev_i32_e32 v0, 6, v1
	v_lshl_add_u32 v168, s4, 3, v0
	v_cmp_gt_i32_e32 vcc, s0, v168
	s_and_saveexec_b64 s[10:11], vcc
	s_cbranch_execz .LBB0_969
	s_load_dwordx2 s[12:13], s[6:7], 0xf0
	s_load_dwordx4 s[28:31], s[6:7], 0x80
	s_lshl_b32 s27, s2, 3
	s_mul_i32 s80, s26, 0x60
	v_and_b32_e32 v170, 7, v1
	s_waitcnt lgkmcnt(0)
	s_add_u32 s14, s12, 0xb500000
	s_addc_u32 s15, s13, 0
	s_add_u32 s16, s12, 0x13d00000
	s_addc_u32 s17, s13, 0
	s_add_u32 s18, s12, 0x17000000
	s_addc_u32 s19, s13, 0
	s_add_u32 s20, s12, 0x1a300000
	s_addc_u32 s21, s13, 0
	s_lshl_b64 s[6:7], s[80:81], 2
	s_add_u32 s22, s28, s6
	s_addc_u32 s23, s29, s7
	s_add_u32 s24, s30, s6
	v_lshlrev_b32_e32 v188, 8, v170
	s_addc_u32 s25, s31, s7
	v_and_b32_e32 v4, 63, v1
	v_lshl_add_u64 v[2:3], s[12:13], 0, v[188:189]
	s_mov_b64 s[6:7], 0xf900000
	v_lshl_add_u64 v[112:113], v[2:3], 0, s[6:7]
	v_lshlrev_b32_e32 v3, 2, v4
	v_xor_b32_e32 v171, 4, v3
	v_xor_b32_e32 v172, 8, v3
	v_xor_b32_e32 v173, 16, v3
	v_lshlrev_b32_e32 v188, 6, v170
	v_mul_u32_u24_e32 v3, 0x60, v170
	v_lshl_add_u64 v[4:5], s[12:13], 0, v[188:189]
	s_mov_b64 s[6:7], 0xa400000
	v_lshlrev_b32_e32 v188, 1, v3
	v_bfe_u32 v169, v1, 3, 3
	v_lshlrev_b32_e32 v2, 1, v170
	v_lshl_add_u64 v[114:115], v[4:5], 0, s[6:7]
	v_lshl_add_u64 v[4:5], s[12:13], 0, v[188:189]
	s_mov_b64 s[6:7], 0xc600000
	v_and_b32_e32 v1, 64, v1
	v_lshlrev_b32_e32 v0, 2, v0
	v_lshl_add_u64 v[116:117], v[4:5], 0, s[6:7]
	v_cmp_ne_u32_e32 vcc, 0, v1
	v_lshl_add_u32 v174, s4, 5, v0
	s_lshl_b32 s36, s2, 5
	s_mov_b64 s[28:29], 0
	v_lshlrev_b32_e32 v118, 4, v2
	v_mbcnt_lo_u32_b32 v0, -1, 0
	v_mbcnt_hi_u32_b32 v0, -1, v0
	v_lshlrev_b32_e32 v1, 4, v0
	v_cmp_gt_u32_e64 s[6:7], 24, v0
	v_subrev_u32_e32 v2, 0x180, v1
	v_mov_b32_e32 v4, s24
	v_mov_b32_e32 v5, s25
	v_mov_b32_e32 v6, s22
	v_mov_b32_e32 v7, s23
	s_nop 0
	v_cndmask_b32_e64 v2, v2, v1, s[6:7]
	v_cndmask_b32_e64 v4, v6, v4, s[6:7]
	v_cndmask_b32_e64 v5, v7, v5, s[6:7]
	v_mov_b32_e32 v3, 0
	v_lshl_add_u64 v[4:5], v[4:5], 0, v[2:3]
	v_cmp_gt_u32_e64 s[6:7], 48, v0
	s_and_saveexec_b64 s[8:9], s[6:7]
	global_load_dwordx4 v[8:11], v[4:5], off
	s_waitcnt vmcnt(0)
	ds_write_b128 v1, v[8:11]
	s_waitcnt lgkmcnt(0)
	s_mov_b64 exec, s[8:9]
	s_branch .LBB0_965
.LBB0_964:
	s_or_b64 exec, exec, s[30:31]
	s_waitcnt lgkmcnt(0)
	v_cvt_pk_bf16_f32 v0, v58, v59
	v_cvt_pk_bf16_f32 v1, v34, v35
	v_cvt_pk_bf16_f32 v2, v76, v77
	v_cvt_pk_bf16_f32 v3, v38, v39
	global_store_dwordx4 v[68:69], v[0:3], off offset:128
	v_add_u32_e32 v168, s27, v168
	s_movk_i32 s0, 0x21ff
	v_cvt_pk_bf16_f32 v0, v64, v65
	v_cvt_pk_bf16_f32 v1, v74, v75
	v_cvt_pk_bf16_f32 v2, v78, v79
	v_cvt_pk_bf16_f32 v3, v80, v81
	global_store_dwordx4 v[68:69], v[0:3], off offset:144
	v_cmp_lt_i32_e64 s[6:7], s0, v168
	s_or_b64 s[28:29], s[6:7], s[28:29]
	v_cvt_pk_bf16_f32 v0, v36, v37
	v_cvt_pk_bf16_f32 v1, v32, v33
	v_cvt_pk_bf16_f32 v2, v44, v45
	v_cvt_pk_bf16_f32 v3, v50, v51
	global_store_dwordx4 v[68:69], v[0:3], off offset:160
	v_add_u32_e32 v174, s36, v174
	s_nop 0
	v_cvt_pk_bf16_f32 v0, v66, v67
	v_cvt_pk_bf16_f32 v1, v42, v43
	v_cvt_pk_bf16_f32 v2, v48, v49
	v_cvt_pk_bf16_f32 v3, v40, v41
	global_store_dwordx4 v[68:69], v[0:3], off offset:176
	s_andn2_b64 exec, exec, s[28:29]
	s_cbranch_execz .LBB0_969
.LBB0_965:
	v_and_b32_e32 v0, -8, v174
	v_or_b32_e32 v46, v0, v169
	v_cmp_gt_i32_e64 s[6:7], s74, v46
	v_add_u32_e32 v34, 0xffff8000, v174
	v_ashrrev_i32_e32 v33, 10, v168
	v_cndmask_b32_e64 v1, v238, v239, s[6:7]
	v_bitop3_b32 v32, v1, v0, v169 bitop3:0xe0
	v_lshlrev_b32_e32 v0, 5, v32
	v_cndmask_b32_e64 v0, 0, v0, s[6:7]
	v_lshlrev_b32_e32 v28, 2, v0
	global_load_dwordx4 v[0:3], v28, s[12:13] offset:48
	global_load_dwordx4 v[8:11], v28, s[12:13] offset:32
	global_load_dwordx4 v[16:19], v28, s[12:13] offset:16
	global_load_dwordx4 v[24:27], v28, s[12:13]
	global_load_dwordx4 v[4:7], v28, s[12:13] offset:112
	global_load_dwordx4 v[12:15], v28, s[12:13] offset:96
	global_load_dwordx4 v[20:23], v28, s[12:13] offset:80
	s_nop 0
	global_load_dwordx4 v[28:31], v28, s[12:13] offset:64
	v_lshrrev_b32_e32 v34, 8, v34
	v_cndmask_b32_e64 v33, v34, v33, s[6:7]
	v_add_u32_e32 v34, 0x100, v32
	v_ashrrev_i32_e32 v47, 31, v46
	v_lshl_or_b32 v142, v33, 3, v170
	v_cndmask_b32_e64 v188, v32, v34, s[6:7]
	v_lshlrev_b64 v[52:53], 9, v[46:47]
	s_and_saveexec_b64 s[4:5], vcc
	s_xor_b64 s[30:31], exec, s[4:5]
	s_cbranch_execz .LBB0_967
; DI float shx(float v, int mask, int lane) { return __int_as_float(__builtin_amdgcn_ds_bpermute((lane ^ mask) << 2, __float_as_int(v))); }
; #define SSQ8(W_, ACC_) do { UNPK(W_, e_); ACC_ += (e_[0] * e_[0] + e_[1] * e_[1]) + (e_[2] * e_[2] + e_[3] * e_[3]) + (e_[4] * e_[4] + e_[5] * e_[5]) + (e_[6] * e_[6] + e_[7] * e_[7]); } while (0)
; DI void phase_mla_fin(ArgsP a, int tb_, int l, char* shm, int vcu, int G) {
;     ...
;             const u32x4* pz = (const u32x4*)(zkv + (size_t)m * 256); const u32x4* p = (const u32x4*)(kvraw + (size_t)m * 1024 + h * 128);
;             u32x4 st[2], krp[4], w[8], vw[8];
; #pragma unroll
;             for (int i = 0; i < 2; ++i) st[i] = pz[2 * h + i];
; #pragma unroll
;             for (int i = 0; i < 4; ++i) krp[i] = pz[16 + i];
; #pragma unroll
;             for (int i = 0; i < 8; ++i) { w[i] = p[i]; vw[i] = p[8 + i]; }
;             const float* gkn = gkn0; asm volatile("" : "+s"(gkn));
;             float sskv = 0.f, ss = 0.f, sk = 0.f;
; #pragma unroll
;             for (int i = 0; i < 2; ++i) SSQ8(st[i], sskv);
;             sskv += shx(sskv, 1, lane); sskv += shx(sskv, 2, lane); sskv += shx(sskv, 4, lane);
;             const float rkv = rsqrtf(sskv * (1.f / 128.f) + EPS);
;     ...
;             float cs[16], sn[16];
; #pragma unroll
;             for (int i = 0; i < 4; ++i) { cs[4 * i] = lat ? rc[i].x : 1.f; cs[4 * i + 1] = lat ? rc[i].y : 1.f; cs[4 * i + 2] = lat ? rc[i].z : 1.f; cs[4 * i + 3] = lat ? rc[i].w : 1.f;
;                 sn[4 * i] = lat ? rs[i].x : 0.f; sn[4 * i + 1] = lat ? rs[i].y : 0.f; sn[4 * i + 2] = lat ? rs[i].z : 0.f; sn[4 * i + 3] = lat ? rs[i].w : 0.f; }
	v_lshl_add_u64 v[32:33], s[14:15], 0, v[52:53]
	v_mov_b32_e32 v119, v189
	v_lshl_add_u64 v[36:37], v[32:33], 0, v[118:119]
	global_load_dwordx4 v[120:123], v[36:37], off
	global_load_dwordx4 v[124:127], v[36:37], off offset:16
	global_load_dwordx4 v[48:51], v[32:33], off offset:304
	global_load_dwordx4 v[52:55], v[32:33], off offset:288
	global_load_dwordx4 v[56:59], v[32:33], off offset:272
	global_load_dwordx4 v[60:63], v[32:33], off offset:256
	v_lshlrev_b64 v[34:35], 11, v[46:47]
	v_lshl_add_u64 v[92:93], v[112:113], 0, v[34:35]
	global_load_dwordx4 v[40:43], v[92:93], off offset:16
	global_load_dwordx4 v[44:47], v[92:93], off
	global_load_dwordx4 v[68:71], v[92:93], off offset:48
	global_load_dwordx4 v[76:79], v[92:93], off offset:32
	global_load_dwordx4 v[96:99], v[92:93], off offset:176
	global_load_dwordx4 v[100:103], v[92:93], off offset:160
	global_load_dwordx4 v[104:107], v[92:93], off offset:144
	global_load_dwordx4 v[108:111], v[92:93], off offset:128
	global_load_dwordx4 v[32:35], v[92:93], off offset:112
	global_load_dwordx4 v[36:39], v[92:93], off offset:96
	global_load_dwordx4 v[64:67], v[92:93], off offset:80
	global_load_dwordx4 v[72:75], v[92:93], off offset:64
	global_load_dwordx4 v[80:83], v[92:93], off offset:240
	global_load_dwordx4 v[84:87], v[92:93], off offset:224
	global_load_dwordx4 v[88:91], v[92:93], off offset:208
	s_nop 0
	global_load_dwordx4 v[92:95], v[92:93], off offset:192
	s_mov_b32 s2, 0x88000
	s_mov_b64 s[34:35], s[24:25]
	s_waitcnt vmcnt(0)
	v_cndmask_b32_e64 v25, 1.0, v25, s[6:7]
	v_cndmask_b32_e64 v24, 1.0, v24, s[6:7]
	v_cndmask_b32_e64 v29, 0, v29, s[6:7]
	v_cndmask_b32_e64 v28, 0, v28, s[6:7]
	v_cndmask_b32_e64 v27, 1.0, v27, s[6:7]
	v_cndmask_b32_e64 v26, 1.0, v26, s[6:7]
	v_cndmask_b32_e64 v31, 0, v31, s[6:7]
	v_cndmask_b32_e64 v30, 0, v30, s[6:7]
	v_cndmask_b32_e64 v17, 1.0, v17, s[6:7]
	v_cndmask_b32_e64 v16, 1.0, v16, s[6:7]
	v_cndmask_b32_e64 v21, 0, v21, s[6:7]
	v_cndmask_b32_e64 v20, 0, v20, s[6:7]
	v_cndmask_b32_e64 v19, 1.0, v19, s[6:7]
	v_cndmask_b32_e64 v18, 1.0, v18, s[6:7]
	v_cndmask_b32_e64 v23, 0, v23, s[6:7]
	v_cndmask_b32_e64 v22, 0, v22, s[6:7]
	v_cndmask_b32_e64 v9, 1.0, v9, s[6:7]
	v_cndmask_b32_e64 v8, 1.0, v8, s[6:7]
	v_cndmask_b32_e64 v13, 0, v13, s[6:7]
	v_cndmask_b32_e64 v12, 0, v12, s[6:7]
	v_cndmask_b32_e64 v11, 1.0, v11, s[6:7]
	v_cndmask_b32_e64 v10, 1.0, v10, s[6:7]
	v_cndmask_b32_e64 v15, 0, v15, s[6:7]
	v_cndmask_b32_e64 v14, 0, v14, s[6:7]
	v_lshlrev_b32_e32 v156, 16, v45
	v_and_b32_e32 v157, 0xffff0000, v45
	v_lshlrev_b32_e32 v158, 16, v44
	v_and_b32_e32 v159, 0xffff0000, v44
	v_lshlrev_b32_e32 v150, 16, v47
	v_and_b32_e32 v151, 0xffff0000, v47
	v_and_b32_e32 v130, 0xffff0000, v120
	v_lshlrev_b32_e32 v129, 16, v124
	v_and_b32_e32 v131, 0xffff0000, v124
	v_lshlrev_b32_e32 v133, 16, v125
	v_and_b32_e32 v125, 0xffff0000, v125
	v_and_b32_e32 v124, 0xffff0000, v121
	v_lshlrev_b32_e32 v128, 16, v120
	v_lshlrev_b32_e32 v132, 16, v121
	v_lshlrev_b32_e32 v121, 16, v126
	v_lshlrev_b32_e32 v120, 16, v122
	v_and_b32_e32 v135, 0xffff0000, v126
	v_and_b32_e32 v134, 0xffff0000, v122
	v_lshlrev_b32_e32 v136, 16, v123
	v_and_b32_e32 v126, 0xffff0000, v123
	v_pk_mul_f32 v[122:123], v[130:131], v[130:131]
	v_pk_mul_f32 v[124:125], v[124:125], v[124:125]
	v_pk_fma_f32 v[122:123], v[128:129], v[128:129], v[122:123]
	v_pk_fma_f32 v[124:125], v[132:133], v[132:133], v[124:125]
	v_lshlrev_b32_e32 v137, 16, v127
	v_pk_add_f32 v[122:123], v[122:123], v[124:125]
	v_pk_mul_f32 v[124:125], v[134:135], v[134:135]
	v_and_b32_e32 v127, 0xffff0000, v127
	v_pk_fma_f32 v[120:121], v[120:121], v[120:121], v[124:125]
	v_and_b32_e32 v124, 0xffff0000, v109
	v_pk_add_f32 v[120:121], v[120:121], v[122:123]
	v_pk_mul_f32 v[122:123], v[126:127], v[126:127]
	v_lshlrev_b32_e32 v125, 16, v110
	v_pk_fma_f32 v[122:123], v[136:137], v[136:137], v[122:123]
	v_and_b32_e32 v110, 0xffff0000, v110
	v_pk_add_f32 v[120:121], v[122:123], v[120:121]
	v_lshlrev_b32_e32 v122, 1, v188
	v_add_f32_e32 v119, v120, v121
	v_mov_b32_e32 v123, v189
	v_lshlrev_b32_e32 v126, 16, v111
	v_and_b32_e32 v111, 0xffff0000, v111
	v_and_b32_e32 v127, 0xffff0000, v68
	s_waitcnt lgkmcnt(0)
	s_nop 1
	v_add_f32_dpp v119, v119, v119 quad_perm:[1,0,3,2] row_mask:0xf bank_mask:0xf
	v_and_b32_e32 v131, 0xffff0000, v72
	v_and_b32_e32 v130, 0xffff0000, v74
	v_and_b32_e32 v133, 0xffff0000, v64
	v_and_b32_e32 v132, 0xffff0000, v66
	s_waitcnt lgkmcnt(0)
	s_nop 1
	v_add_f32_dpp v119, v119, v119 quad_perm:[2,3,0,1] row_mask:0xf bank_mask:0xf
	v_lshlrev_b32_e32 v154, 16, v46
	v_and_b32_e32 v155, 0xffff0000, v46
	s_waitcnt lgkmcnt(0)
; DI bf16_t f2bf(float f) { return (bf16_t)(cvtpk(f, f) & 0xffffu); }
; #define UNPK(W_, E_) const float E_[8] = {bflo((W_).x), bfhi((W_).x), bflo((W_).y), bfhi((W_).y), bflo((W_).z), bfhi((W_).z), bflo((W_).w), bfhi((W_).w)}
; DI void phase_mla_fin(ArgsP a, int tb_, int l, char* shm, int vcu, int G) {
;     ...
;             const float rkv = rsqrtf(sskv * (1.f / 128.f) + EPS);
;             { bf16_t* vo = Vt + bh * 64 * KVLEN + pos;
; #pragma unroll
;               for (int i = 0; i < 8; ++i) { UNPK(vw[i], e);
; #pragma unroll
;                   for (int j = 0; j < 8; ++j) vo[(size_t)(8 * i + j) * KVLEN] = f2bf(e[j] * rkv); } }
	s_nop 1
	v_add_f32_dpp v119, v119, v119 row_half_mirror row_mask:0xf bank_mask:0xf
	v_fmamk_f32 v119, v119, 0x3c000000, v230
	v_cmp_gt_f32_e64 s[8:9], s76, v119
	v_mul_f32_e32 v120, 0x4b800000, v119
	s_nop 0
	v_cndmask_b32_e64 v119, v119, v120, s[8:9]
	v_rsq_f32_e32 v119, v119
	s_nop 0
	v_mul_f32_e32 v120, 0x45800000, v119
	v_cndmask_b32_e64 v119, v119, v120, s[8:9]
	v_mov_b64_e32 v[120:121], s[20:21]
	v_mad_i64_i32 v[120:121], s[4:5], v142, s2, v[120:121]
	v_lshl_add_u64 v[120:121], v[120:121], 0, v[122:123]
	v_lshlrev_b32_e32 v122, 16, v108
	v_and_b32_e32 v108, 0xffff0000, v108
	v_lshlrev_b32_e32 v123, 16, v109
	v_mul_f32_e32 v109, v119, v122
	v_mul_f32_e32 v108, v119, v108
	s_movk_i32 s2, 0x2000
	v_cvt_pk_bf16_f32 v109, v109, s0
	v_cvt_pk_bf16_f32 v122, v108, s0
	v_add_co_u32_e64 v108, s[8:9], s2, v120
	global_store_short v[120:121], v109, off
	s_nop 0
	v_addc_co_u32_e64 v109, s[8:9], 0, v121, s[8:9]
	global_store_short v[108:109], v122, off offset:512
	v_mul_f32_e32 v108, v119, v123
	v_cvt_pk_bf16_f32 v122, v108, s0
	s_movk_i32 s0, 0x4000
	v_add_co_u32_e64 v108, s[8:9], s0, v120
	s_movk_i32 s2, 0x6000
	s_nop 0
	v_addc_co_u32_e64 v109, s[8:9], 0, v121, s[8:9]
	global_store_short v[108:109], v122, off offset:1024
	v_mul_f32_e32 v108, v119, v124
	v_cvt_pk_bf16_f32 v122, v108, s0
	v_add_co_u32_e64 v108, s[8:9], s2, v120
	s_mov_b32 s2, 0xa000
	s_nop 0
	v_addc_co_u32_e64 v109, s[8:9], 0, v121, s[8:9]
	global_store_short v[108:109], v122, off offset:1536
	v_mul_f32_e32 v108, v119, v125
	v_cvt_pk_bf16_f32 v122, v108, s0
	v_add_co_u32_e64 v108, s[8:9], s74, v120
	v_lshlrev_b32_e32 v123, 16, v107
	s_nop 0
	v_addc_co_u32_e64 v109, s[8:9], 0, v121, s[8:9]
	global_store_short v[108:109], v122, off offset:2048
	v_mul_f32_e32 v108, v119, v110
	v_cvt_pk_bf16_f32 v110, v108, s0
	v_add_co_u32_e64 v108, s[8:9], s2, v120
	s_mov_b32 s2, 0xe000
	s_nop 0
	v_addc_co_u32_e64 v109, s[8:9], 0, v121, s[8:9]
	global_store_short v[108:109], v110, off offset:2560
	v_mul_f32_e32 v108, v119, v126
	v_cvt_pk_bf16_f32 v110, v108, s0
	s_mov_b32 s0, 0xc000
	v_add_co_u32_e64 v108, s[8:9], s0, v120
	v_lshlrev_b32_e32 v122, 16, v106
	s_nop 0
	v_addc_co_u32_e64 v109, s[8:9], 0, v121, s[8:9]
	global_store_short v[108:109], v110, off offset:3072
	v_mul_f32_e32 v108, v119, v111
	v_cvt_pk_bf16_f32 v110, v108, s0
	v_add_co_u32_e64 v108, s[8:9], s2, v120
	s_mov_b32 s2, 0x11000
	s_nop 0
	v_addc_co_u32_e64 v109, s[8:9], 0, v121, s[8:9]
	global_store_short v[108:109], v110, off offset:3584
	v_lshlrev_b32_e32 v108, 16, v104
	v_and_b32_e32 v109, 0xffff0000, v104
	v_mul_f32_e32 v104, v119, v108
	v_cvt_pk_bf16_f32 v108, v104, s0
	v_add_co_u32_e64 v104, s[8:9], s2, v120
	v_lshlrev_b32_e32 v110, 16, v105
	v_and_b32_e32 v111, 0xffff0000, v105
	v_addc_co_u32_e64 v105, s[8:9], 0, v121, s[8:9]
	global_store_short v[104:105], v108, off
	v_mul_f32_e32 v104, v119, v109
	s_mov_b32 s2, 0x13000
	v_cvt_pk_bf16_f32 v108, v104, s0
	v_add_co_u32_e64 v104, s[8:9], s2, v120
	s_mov_b32 s2, 0x15000
	s_nop 0
	v_addc_co_u32_e64 v105, s[8:9], 0, v121, s[8:9]
	global_store_short v[104:105], v108, off offset:512
	v_mul_f32_e32 v104, v119, v110
	v_cvt_pk_bf16_f32 v108, v104, s0
	v_add_co_u32_e64 v104, s[8:9], s2, v120
	s_mov_b32 s2, 0x17000
	s_nop 0
	v_addc_co_u32_e64 v105, s[8:9], 0, v121, s[8:9]
	global_store_short v[104:105], v108, off offset:1024
	v_mul_f32_e32 v104, v119, v111
	v_cvt_pk_bf16_f32 v108, v104, s0
	v_add_co_u32_e64 v104, s[8:9], s2, v120
	s_mov_b32 s2, 0x19000
	s_nop 0
	v_addc_co_u32_e64 v105, s[8:9], 0, v121, s[8:9]
	global_store_short v[104:105], v108, off offset:1536
	v_mul_f32_e32 v104, v119, v122
	v_cvt_pk_bf16_f32 v108, v104, s0
	v_add_co_u32_e64 v104, s[8:9], s2, v120
	v_and_b32_e32 v106, 0xffff0000, v106
	s_nop 0
	v_addc_co_u32_e64 v105, s[8:9], 0, v121, s[8:9]
	global_store_short v[104:105], v108, off offset:2048
	v_mul_f32_e32 v104, v119, v106
	v_cvt_pk_bf16_f32 v106, v104, s0
	v_add_co_u32_e64 v104, s[8:9], s56, v120
	s_mov_b32 s2, 0x1d000
	s_nop 0
	v_addc_co_u32_e64 v105, s[8:9], 0, v121, s[8:9]
	global_store_short v[104:105], v106, off offset:2560
	v_mul_f32_e32 v104, v119, v123
	v_cvt_pk_bf16_f32 v106, v104, s0
	v_add_co_u32_e64 v104, s[8:9], s2, v120
	v_and_b32_e32 v107, 0xffff0000, v107
	s_nop 0
	v_addc_co_u32_e64 v105, s[8:9], 0, v121, s[8:9]
	global_store_short v[104:105], v106, off offset:3072
	v_mul_f32_e32 v104, v119, v107
	s_mov_b32 s2, 0x1f000
	v_cvt_pk_bf16_f32 v106, v104, s0
	v_add_co_u32_e64 v104, s[8:9], s2, v120
	s_mov_b32 s2, 0x22000
	s_nop 0
	v_addc_co_u32_e64 v105, s[8:9], 0, v121, s[8:9]
	global_store_short v[104:105], v106, off offset:3584
	v_lshlrev_b32_e32 v104, 16, v100
	v_and_b32_e32 v105, 0xffff0000, v100
	v_mul_f32_e32 v100, v119, v104
	v_cvt_pk_bf16_f32 v104, v100, s0
	v_add_co_u32_e64 v100, s[8:9], s2, v120
	v_lshlrev_b32_e32 v106, 16, v101
	v_and_b32_e32 v107, 0xffff0000, v101
	v_addc_co_u32_e64 v101, s[8:9], 0, v121, s[8:9]
	global_store_short v[100:101], v104, off
	v_mul_f32_e32 v100, v119, v105
	v_cvt_pk_bf16_f32 v104, v100, s0
	s_mov_b32 s0, 0x24000
	v_add_co_u32_e64 v100, s[8:9], s0, v120
	s_mov_b32 s2, 0x26000
	s_nop 0
	v_addc_co_u32_e64 v101, s[8:9], 0, v121, s[8:9]
	global_store_short v[100:101], v104, off offset:512
	v_mul_f32_e32 v100, v119, v106
	v_cvt_pk_bf16_f32 v104, v100, s0
	v_add_co_u32_e64 v100, s[8:9], s2, v120
	v_lshlrev_b32_e32 v108, 16, v102
	s_nop 0
	v_addc_co_u32_e64 v101, s[8:9], 0, v121, s[8:9]
	global_store_short v[100:101], v104, off offset:1024
	v_mul_f32_e32 v100, v119, v107
	v_cvt_pk_bf16_f32 v104, v100, s0
	s_mov_b32 s0, 0x28000
	v_add_co_u32_e64 v100, s[8:9], s0, v120
	s_mov_b32 s2, 0x2a000
	s_nop 0
; DI bf16_t f2bf(float f) { return (bf16_t)(cvtpk(f, f) & 0xffffu); }
; #define UNPK(W_, E_) const float E_[8] = {bflo((W_).x), bfhi((W_).x), bflo((W_).y), bfhi((W_).y), bflo((W_).z), bfhi((W_).z), bflo((W_).w), bfhi((W_).w)}
; DI void phase_mla_fin(ArgsP a, int tb_, int l, char* shm, int vcu, int G) {
;     ...
;             { bf16_t* vo = Vt + bh * 64 * KVLEN + pos;
; #pragma unroll
;               for (int i = 0; i < 8; ++i) { UNPK(vw[i], e);
; #pragma unroll
;                   for (int j = 0; j < 8; ++j) vo[(size_t)(8 * i + j) * KVLEN] = f2bf(e[j] * rkv); } }
	v_addc_co_u32_e64 v101, s[8:9], 0, v121, s[8:9]
	global_store_short v[100:101], v104, off offset:1536
	v_mul_f32_e32 v100, v119, v108
	v_cvt_pk_bf16_f32 v104, v100, s0
	v_add_co_u32_e64 v100, s[8:9], s2, v120
	v_and_b32_e32 v102, 0xffff0000, v102
	s_nop 0
	v_addc_co_u32_e64 v101, s[8:9], 0, v121, s[8:9]
	global_store_short v[100:101], v104, off offset:2048
	v_mul_f32_e32 v100, v119, v102
	v_cvt_pk_bf16_f32 v102, v100, s0
	s_mov_b32 s0, 0x2c000
	v_add_co_u32_e64 v100, s[8:9], s0, v120
	v_lshlrev_b32_e32 v109, 16, v103
	s_nop 0
	v_addc_co_u32_e64 v101, s[8:9], 0, v121, s[8:9]
	global_store_short v[100:101], v102, off offset:2560
	v_mul_f32_e32 v100, v119, v109
	s_mov_b32 s2, 0x2e000
	v_cvt_pk_bf16_f32 v102, v100, s0
	v_add_co_u32_e64 v100, s[8:9], s2, v120
	v_and_b32_e32 v103, 0xffff0000, v103
	s_nop 0
	v_addc_co_u32_e64 v101, s[8:9], 0, v121, s[8:9]
	global_store_short v[100:101], v102, off offset:3072
	v_mul_f32_e32 v100, v119, v103
	s_mov_b32 s2, 0x30000
	v_cvt_pk_bf16_f32 v102, v100, s0
	v_add_co_u32_e64 v100, s[8:9], s2, v120
	s_mov_b32 s2, 0x33000
	s_nop 0
	v_addc_co_u32_e64 v101, s[8:9], 0, v121, s[8:9]
	global_store_short v[100:101], v102, off offset:3584
	v_lshlrev_b32_e32 v100, 16, v96
	v_and_b32_e32 v101, 0xffff0000, v96
	v_mul_f32_e32 v96, v119, v100
	v_cvt_pk_bf16_f32 v100, v96, s0
	v_add_co_u32_e64 v96, s[8:9], s2, v120
	v_lshlrev_b32_e32 v102, 16, v97
	v_and_b32_e32 v103, 0xffff0000, v97
	v_addc_co_u32_e64 v97, s[8:9], 0, v121, s[8:9]
	global_store_short v[96:97], v100, off
	v_mul_f32_e32 v96, v119, v101
	s_mov_b32 s2, 0x35000
	v_cvt_pk_bf16_f32 v100, v96, s0
	v_add_co_u32_e64 v96, s[8:9], s2, v120
	s_mov_b32 s2, 0x37000
	s_nop 0
	v_addc_co_u32_e64 v97, s[8:9], 0, v121, s[8:9]
	global_store_short v[96:97], v100, off offset:512
	v_mul_f32_e32 v96, v119, v102
	v_cvt_pk_bf16_f32 v100, v96, s0
	v_add_co_u32_e64 v96, s[8:9], s2, v120
	s_mov_b32 s2, 0x39000
	s_nop 0
	v_addc_co_u32_e64 v97, s[8:9], 0, v121, s[8:9]
	global_store_short v[96:97], v100, off offset:1024
	v_mul_f32_e32 v96, v119, v103
	v_cvt_pk_bf16_f32 v100, v96, s0
	v_add_co_u32_e64 v96, s[8:9], s2, v120
	v_lshlrev_b32_e32 v104, 16, v98
	s_nop 0
	v_addc_co_u32_e64 v97, s[8:9], 0, v121, s[8:9]
	global_store_short v[96:97], v100, off offset:1536
	v_mul_f32_e32 v96, v119, v104
	s_mov_b32 s2, 0x3b000
	v_cvt_pk_bf16_f32 v100, v96, s0
	v_add_co_u32_e64 v96, s[8:9], s2, v120
	v_and_b32_e32 v98, 0xffff0000, v98
	s_nop 0
	v_addc_co_u32_e64 v97, s[8:9], 0, v121, s[8:9]
	global_store_short v[96:97], v100, off offset:2048
	v_mul_f32_e32 v96, v119, v98
	s_mov_b32 s2, 0x3d000
	v_cvt_pk_bf16_f32 v98, v96, s0
	v_add_co_u32_e64 v96, s[8:9], s2, v120
	v_lshlrev_b32_e32 v105, 16, v99
	s_nop 0
	v_addc_co_u32_e64 v97, s[8:9], 0, v121, s[8:9]
	global_store_short v[96:97], v98, off offset:2560
	v_mul_f32_e32 v96, v119, v105
	s_mov_b32 s2, 0x3f000
	v_cvt_pk_bf16_f32 v98, v96, s0
	v_add_co_u32_e64 v96, s[8:9], s2, v120
	v_and_b32_e32 v99, 0xffff0000, v99
	s_nop 0
	v_addc_co_u32_e64 v97, s[8:9], 0, v121, s[8:9]
	global_store_short v[96:97], v98, off offset:3072
	v_mul_f32_e32 v96, v119, v99
	s_mov_b32 s2, 0x41000
	v_cvt_pk_bf16_f32 v98, v96, s0
	v_add_co_u32_e64 v96, s[8:9], s2, v120
	s_mov_b32 s2, 0x44000
	s_nop 0
	v_addc_co_u32_e64 v97, s[8:9], 0, v121, s[8:9]
	global_store_short v[96:97], v98, off offset:3584
	v_lshlrev_b32_e32 v96, 16, v92
	v_and_b32_e32 v97, 0xffff0000, v92
	v_mul_f32_e32 v92, v119, v96
	v_cvt_pk_bf16_f32 v96, v92, s0
	v_add_co_u32_e64 v92, s[8:9], s2, v120
	v_lshlrev_b32_e32 v98, 16, v93
	v_and_b32_e32 v99, 0xffff0000, v93
	v_addc_co_u32_e64 v93, s[8:9], 0, v121, s[8:9]
	global_store_short v[92:93], v96, off
	v_mul_f32_e32 v92, v119, v97
	s_mov_b32 s2, 0x46000
	v_cvt_pk_bf16_f32 v96, v92, s0
	v_add_co_u32_e64 v92, s[8:9], s2, v120
	s_mov_b32 s2, 0x4a000
	s_nop 0
	v_addc_co_u32_e64 v93, s[8:9], 0, v121, s[8:9]
	global_store_short v[92:93], v96, off offset:512
	v_mul_f32_e32 v92, v119, v98
	v_cvt_pk_bf16_f32 v96, v92, s0
	s_mov_b32 s0, 0x48000
	v_add_co_u32_e64 v92, s[8:9], s0, v120
	v_lshlrev_b32_e32 v100, 16, v94
	s_nop 0
	v_addc_co_u32_e64 v93, s[8:9], 0, v121, s[8:9]
	global_store_short v[92:93], v96, off offset:1024
	v_mul_f32_e32 v92, v119, v99
	v_cvt_pk_bf16_f32 v96, v92, s0
	v_add_co_u32_e64 v92, s[8:9], s2, v120
	s_mov_b32 s2, 0x4c000
	s_nop 0
	v_addc_co_u32_e64 v93, s[8:9], 0, v121, s[8:9]
	global_store_short v[92:93], v96, off offset:1536
	v_mul_f32_e32 v92, v119, v100
	v_cvt_pk_bf16_f32 v96, v92, s0
	v_add_co_u32_e64 v92, s[8:9], s2, v120
	v_and_b32_e32 v94, 0xffff0000, v94
	s_nop 0
	v_addc_co_u32_e64 v93, s[8:9], 0, v121, s[8:9]
	global_store_short v[92:93], v96, off offset:2048
	v_mul_f32_e32 v92, v119, v94
	s_mov_b32 s2, 0x4e000
	v_cvt_pk_bf16_f32 v94, v92, s0
	v_add_co_u32_e64 v92, s[8:9], s2, v120
	v_lshlrev_b32_e32 v101, 16, v95
	s_nop 0
	v_addc_co_u32_e64 v93, s[8:9], 0, v121, s[8:9]
	global_store_short v[92:93], v94, off offset:2560
	v_mul_f32_e32 v92, v119, v101
	v_cvt_pk_bf16_f32 v94, v92, s0
	s_mov_b32 s0, 0x50000
	v_add_co_u32_e64 v92, s[8:9], s0, v120
	v_and_b32_e32 v95, 0xffff0000, v95
	s_nop 0
	v_addc_co_u32_e64 v93, s[8:9], 0, v121, s[8:9]
	global_store_short v[92:93], v94, off offset:3072
	v_mul_f32_e32 v92, v119, v95
	s_mov_b32 s2, 0x52000
	v_cvt_pk_bf16_f32 v94, v92, s0
	v_add_co_u32_e64 v92, s[8:9], s2, v120
	s_mov_b32 s2, 0x55000
	s_nop 0
	v_addc_co_u32_e64 v93, s[8:9], 0, v121, s[8:9]
	global_store_short v[92:93], v94, off offset:3584
	v_lshlrev_b32_e32 v92, 16, v88
	v_and_b32_e32 v93, 0xffff0000, v88
	v_mul_f32_e32 v88, v119, v92
	v_cvt_pk_bf16_f32 v92, v88, s0
	v_add_co_u32_e64 v88, s[8:9], s2, v120
	v_lshlrev_b32_e32 v94, 16, v89
; DI bf16_t f2bf(float f) { return (bf16_t)(cvtpk(f, f) & 0xffffu); }
; #define UNPK(W_, E_) const float E_[8] = {bflo((W_).x), bfhi((W_).x), bflo((W_).y), bfhi((W_).y), bflo((W_).z), bfhi((W_).z), bflo((W_).w), bfhi((W_).w)}
; DI void phase_mla_fin(ArgsP a, int tb_, int l, char* shm, int vcu, int G) {
;     ...
;             { bf16_t* vo = Vt + bh * 64 * KVLEN + pos;
; #pragma unroll
;               for (int i = 0; i < 8; ++i) { UNPK(vw[i], e);
; #pragma unroll
;                   for (int j = 0; j < 8; ++j) vo[(size_t)(8 * i + j) * KVLEN] = f2bf(e[j] * rkv); } }
	v_and_b32_e32 v95, 0xffff0000, v89
	v_addc_co_u32_e64 v89, s[8:9], 0, v121, s[8:9]
	global_store_short v[88:89], v92, off
	v_mul_f32_e32 v88, v119, v93
	s_mov_b32 s2, 0x57000
	v_cvt_pk_bf16_f32 v92, v88, s0
	v_add_co_u32_e64 v88, s[8:9], s2, v120
	s_mov_b32 s2, 0x59000
	s_nop 0
	v_addc_co_u32_e64 v89, s[8:9], 0, v121, s[8:9]
	global_store_short v[88:89], v92, off offset:512
	v_mul_f32_e32 v88, v119, v94
	v_cvt_pk_bf16_f32 v92, v88, s0
	v_add_co_u32_e64 v88, s[8:9], s2, v120
	s_mov_b32 s2, 0x5b000
	s_nop 0
	v_addc_co_u32_e64 v89, s[8:9], 0, v121, s[8:9]
	global_store_short v[88:89], v92, off offset:1024
	v_mul_f32_e32 v88, v119, v95
	v_cvt_pk_bf16_f32 v92, v88, s0
	v_add_co_u32_e64 v88, s[8:9], s2, v120
	v_lshlrev_b32_e32 v96, 16, v90
	s_nop 0
	v_addc_co_u32_e64 v89, s[8:9], 0, v121, s[8:9]
	global_store_short v[88:89], v92, off offset:1536
	v_mul_f32_e32 v88, v119, v96
	s_mov_b32 s2, 0x5d000
	v_cvt_pk_bf16_f32 v92, v88, s0
	v_add_co_u32_e64 v88, s[8:9], s2, v120
	v_and_b32_e32 v90, 0xffff0000, v90
	s_nop 0
	v_addc_co_u32_e64 v89, s[8:9], 0, v121, s[8:9]
	global_store_short v[88:89], v92, off offset:2048
	v_mul_f32_e32 v88, v119, v90
	s_mov_b32 s2, 0x5f000
	v_cvt_pk_bf16_f32 v90, v88, s0
	v_add_co_u32_e64 v88, s[8:9], s2, v120
	v_lshlrev_b32_e32 v97, 16, v91
	s_nop 0
	v_addc_co_u32_e64 v89, s[8:9], 0, v121, s[8:9]
	global_store_short v[88:89], v90, off offset:2560
	v_mul_f32_e32 v88, v119, v97
	s_mov_b32 s2, 0x61000
	v_cvt_pk_bf16_f32 v90, v88, s0
	v_add_co_u32_e64 v88, s[8:9], s2, v120
	v_and_b32_e32 v91, 0xffff0000, v91
	s_nop 0
	v_addc_co_u32_e64 v89, s[8:9], 0, v121, s[8:9]
	global_store_short v[88:89], v90, off offset:3072
	v_mul_f32_e32 v88, v119, v91
	s_mov_b32 s2, 0x63000
	v_cvt_pk_bf16_f32 v90, v88, s0
	v_add_co_u32_e64 v88, s[8:9], s2, v120
	s_mov_b32 s2, 0x66000
	s_nop 0
	v_addc_co_u32_e64 v89, s[8:9], 0, v121, s[8:9]
	global_store_short v[88:89], v90, off offset:3584
	v_lshlrev_b32_e32 v88, 16, v84
	v_and_b32_e32 v89, 0xffff0000, v84
	v_mul_f32_e32 v84, v119, v88
	v_cvt_pk_bf16_f32 v88, v84, s0
	v_add_co_u32_e64 v84, s[8:9], s2, v120
	v_lshlrev_b32_e32 v90, 16, v85
	v_and_b32_e32 v91, 0xffff0000, v85
	v_addc_co_u32_e64 v85, s[8:9], 0, v121, s[8:9]
	global_store_short v[84:85], v88, off
	v_mul_f32_e32 v84, v119, v89
	s_mov_b32 s2, 0x68000
	v_cvt_pk_bf16_f32 v88, v84, s0
	v_add_co_u32_e64 v84, s[8:9], s2, v120
	s_mov_b32 s2, 0x6a000
	s_nop 0
	v_addc_co_u32_e64 v85, s[8:9], 0, v121, s[8:9]
	global_store_short v[84:85], v88, off offset:512
	v_mul_f32_e32 v84, v119, v90
	v_cvt_pk_bf16_f32 v88, v84, s0
	v_add_co_u32_e64 v84, s[8:9], s2, v120
	s_mov_b32 s2, 0x6c000
	s_nop 0
	v_addc_co_u32_e64 v85, s[8:9], 0, v121, s[8:9]
	global_store_short v[84:85], v88, off offset:1024
	v_mul_f32_e32 v84, v119, v91
	v_cvt_pk_bf16_f32 v88, v84, s0
	v_add_co_u32_e64 v84, s[8:9], s2, v120
	v_lshlrev_b32_e32 v92, 16, v86
	s_nop 0
	v_addc_co_u32_e64 v85, s[8:9], 0, v121, s[8:9]
	global_store_short v[84:85], v88, off offset:1536
	v_mul_f32_e32 v84, v119, v92
	s_mov_b32 s2, 0x6e000
	v_cvt_pk_bf16_f32 v88, v84, s0
	v_add_co_u32_e64 v84, s[8:9], s2, v120
	v_and_b32_e32 v86, 0xffff0000, v86
	s_nop 0
	v_addc_co_u32_e64 v85, s[8:9], 0, v121, s[8:9]
	global_store_short v[84:85], v88, off offset:2048
	v_mul_f32_e32 v84, v119, v86
	s_mov_b32 s2, 0x70000
	v_cvt_pk_bf16_f32 v86, v84, s0
	v_add_co_u32_e64 v84, s[8:9], s2, v120
	v_lshlrev_b32_e32 v93, 16, v87
	s_nop 0
	v_addc_co_u32_e64 v85, s[8:9], 0, v121, s[8:9]
	global_store_short v[84:85], v86, off offset:2560
	v_mul_f32_e32 v84, v119, v93
	s_mov_b32 s2, 0x72000
	v_cvt_pk_bf16_f32 v86, v84, s0
	v_add_co_u32_e64 v84, s[8:9], s2, v120
	v_and_b32_e32 v87, 0xffff0000, v87
	s_nop 0
	v_addc_co_u32_e64 v85, s[8:9], 0, v121, s[8:9]
	global_store_short v[84:85], v86, off offset:3072
	v_mul_f32_e32 v84, v119, v87
	s_mov_b32 s2, 0x74000
	v_cvt_pk_bf16_f32 v86, v84, s0
	v_add_co_u32_e64 v84, s[8:9], s2, v120
	s_mov_b32 s2, 0x77000
	s_nop 0
	v_addc_co_u32_e64 v85, s[8:9], 0, v121, s[8:9]
	global_store_short v[84:85], v86, off offset:3584
	v_lshlrev_b32_e32 v84, 16, v80
	v_and_b32_e32 v85, 0xffff0000, v80
	v_mul_f32_e32 v80, v119, v84
	v_cvt_pk_bf16_f32 v84, v80, s0
	v_add_co_u32_e64 v80, s[8:9], s2, v120
	v_lshlrev_b32_e32 v86, 16, v81
	v_and_b32_e32 v87, 0xffff0000, v81
	v_addc_co_u32_e64 v81, s[8:9], 0, v121, s[8:9]
	global_store_short v[80:81], v84, off
	v_mul_f32_e32 v80, v119, v85
	s_mov_b32 s2, 0x79000
	v_cvt_pk_bf16_f32 v84, v80, s0
	v_add_co_u32_e64 v80, s[8:9], s2, v120
	s_mov_b32 s2, 0x7b000
	s_nop 0
	v_addc_co_u32_e64 v81, s[8:9], 0, v121, s[8:9]
	global_store_short v[80:81], v84, off offset:512
	v_mul_f32_e32 v80, v119, v86
	v_cvt_pk_bf16_f32 v84, v80, s0
	v_add_co_u32_e64 v80, s[8:9], s2, v120
	s_mov_b32 s2, 0x7d000
	s_nop 0
	v_addc_co_u32_e64 v81, s[8:9], 0, v121, s[8:9]
	global_store_short v[80:81], v84, off offset:1024
	v_mul_f32_e32 v80, v119, v87
	v_cvt_pk_bf16_f32 v84, v80, s0
	v_add_co_u32_e64 v80, s[8:9], s2, v120
	v_lshlrev_b32_e32 v88, 16, v82
	s_nop 0
	v_addc_co_u32_e64 v81, s[8:9], 0, v121, s[8:9]
	global_store_short v[80:81], v84, off offset:1536
	v_mul_f32_e32 v80, v119, v88
	s_mov_b32 s2, 0x7f000
	v_cvt_pk_bf16_f32 v84, v80, s0
	v_add_co_u32_e64 v80, s[8:9], s2, v120
	v_and_b32_e32 v82, 0xffff0000, v82
	s_nop 0
	v_addc_co_u32_e64 v81, s[8:9], 0, v121, s[8:9]
	global_store_short v[80:81], v84, off offset:2048
	v_mul_f32_e32 v80, v119, v82
	s_mov_b32 s2, 0x81000
	v_cvt_pk_bf16_f32 v82, v80, s0
	v_add_co_u32_e64 v80, s[8:9], s2, v120
	v_lshlrev_b32_e32 v89, 16, v83
	s_nop 0
	v_addc_co_u32_e64 v81, s[8:9], 0, v121, s[8:9]
	global_store_short v[80:81], v82, off offset:2560
	v_mul_f32_e32 v80, v119, v89
; DI unsigned cvtpk(float lo, float hi) { f32x2_t v = {lo, hi}; bf16x2_t b = __builtin_convertvector(v, bf16x2_t); return __builtin_bit_cast(unsigned, b); }
; DI bf16_t f2bf(float f) { return (bf16_t)(cvtpk(f, f) & 0xffffu); }
; #define UNPK(W_, E_) const float E_[8] = {bflo((W_).x), bfhi((W_).x), bflo((W_).y), bfhi((W_).y), bflo((W_).z), bfhi((W_).z), bflo((W_).w), bfhi((W_).w)}
; #define SSQ8(W_, ACC_) do { UNPK(W_, e_); ACC_ += (e_[0] * e_[0] + e_[1] * e_[1]) + (e_[2] * e_[2] + e_[3] * e_[3]) + (e_[4] * e_[4] + e_[5] * e_[5]) + (e_[6] * e_[6] + e_[7] * e_[7]); } while (0)
; DI void phase_mla_fin(ArgsP a, int tb_, int l, char* shm, int vcu, int G) {
;     ...
;                   for (int j = 0; j < 8; ++j) vo[(size_t)(8 * i + j) * KVLEN] = f2bf(e[j] * rkv); } }
; #pragma unroll
;             for (int i = 0; i < 8; ++i) SSQ8(w[i], ss);
; #pragma unroll
;             for (int i = 0; i < 4; ++i) SSQ8(krp[i], sk);
;             const float rn = rsqrtf((ss * rkv * rkv + sk) * (1.f / 96.f) + EPS);
;             u32x4* o = (u32x4*)(Kb + (bh * KVLEN + pos) * 96);
; #pragma unroll
;             for (int i = 0; i < 8; ++i) { UNPK(w[i], e); const float sc = rn * rkv; u32x4 ow;
;                 ow.x = cvtpk(e[0] * sc * gkn[8 * i], e[1] * sc * gkn[8 * i + 1]); ow.y = cvtpk(e[2] * sc * gkn[8 * i + 2], e[3] * sc * gkn[8 * i + 3]);
;                 ow.z = cvtpk(e[4] * sc * gkn[8 * i + 4], e[5] * sc * gkn[8 * i + 5]); ow.w = cvtpk(e[6] * sc * gkn[8 * i + 6], e[7] * sc * gkn[8 * i + 7]); o[i] = ow; }
	s_mov_b32 s2, 0x83000
	v_cvt_pk_bf16_f32 v82, v80, s0
	v_add_co_u32_e64 v80, s[8:9], s2, v120
	v_and_b32_e32 v83, 0xffff0000, v83
	s_nop 0
	v_addc_co_u32_e64 v81, s[8:9], 0, v121, s[8:9]
	global_store_short v[80:81], v82, off offset:3072
	v_mul_f32_e32 v80, v119, v83
	s_mov_b32 s2, 0x85000
	v_cvt_pk_bf16_f32 v82, v80, s0
	v_add_co_u32_e64 v80, s[8:9], s2, v120
	v_and_b32_e32 v120, 0xffff0000, v76
	s_nop 0
	v_addc_co_u32_e64 v81, s[8:9], 0, v121, s[8:9]
	v_and_b32_e32 v121, 0xffff0000, v77
	v_lshlrev_b32_e32 v123, 16, v77
	v_lshlrev_b32_e32 v122, 16, v76
	v_pk_mul_f32 v[76:77], v[120:121], v[120:121]
	v_and_b32_e32 v111, 0xffff0000, v79
	v_and_b32_e32 v110, 0xffff0000, v78
	v_pk_fma_f32 v[76:77], v[122:123], v[122:123], v[76:77]
	v_lshlrev_b32_e32 v125, 16, v79
	v_lshlrev_b32_e32 v124, 16, v78
	v_pk_mul_f32 v[78:79], v[110:111], v[110:111]
	v_add_f32_e32 v76, v76, v77
	v_pk_fma_f32 v[78:79], v[124:125], v[124:125], v[78:79]
	v_and_b32_e32 v107, 0xffff0000, v69
	v_add_f32_e32 v76, v78, v76
	v_and_b32_e32 v126, 0xffff0000, v70
	v_pk_add_f32 v[128:129], v[78:79], v[76:77] op_sel_hi:[1,0]
	v_lshlrev_b32_e32 v106, 16, v69
	v_mul_f32_e32 v76, v107, v107
	v_lshlrev_b32_e32 v109, 16, v68
	v_lshlrev_b32_e32 v108, 16, v70
	v_pk_mul_f32 v[68:69], v[126:127], v[126:127]
	v_pk_fma_f32 v[76:77], v[106:107], v[106:107], v[76:77] op_sel_hi:[1,1,0]
	v_pk_fma_f32 v[68:69], v[108:109], v[108:109], v[68:69]
	v_lshlrev_b32_e32 v104, 16, v71
	v_pk_add_f32 v[76:77], v[68:69], v[76:77] op_sel:[1,0] op_sel_hi:[0,1]
	v_pk_add_f32 v[134:135], v[68:69], v[76:77]
	v_and_b32_e32 v105, 0xffff0000, v71
	v_mul_f32_e32 v68, v104, v104
	v_and_b32_e32 v101, 0xffff0000, v73
	v_pk_fma_f32 v[136:137], v[104:105], v[104:105], v[68:69] op_sel_hi:[1,1,0]
	v_lshlrev_b32_e32 v100, 16, v73
	v_mul_f32_e32 v68, v101, v101
	v_lshlrev_b32_e32 v103, 16, v72
	v_lshlrev_b32_e32 v102, 16, v74
	v_pk_mul_f32 v[70:71], v[130:131], v[130:131]
	v_pk_fma_f32 v[68:69], v[100:101], v[100:101], v[68:69] op_sel_hi:[1,1,0]
	v_pk_fma_f32 v[70:71], v[102:103], v[102:103], v[70:71]
	v_lshlrev_b32_e32 v98, 16, v75
	v_pk_add_f32 v[68:69], v[70:71], v[68:69] op_sel:[1,0] op_sel_hi:[0,1]
	v_pk_add_f32 v[138:139], v[70:71], v[68:69]
	v_and_b32_e32 v99, 0xffff0000, v75
	v_mul_f32_e32 v68, v98, v98
	v_and_b32_e32 v95, 0xffff0000, v65
	v_pk_fma_f32 v[144:145], v[98:99], v[98:99], v[68:69] op_sel_hi:[1,1,0]
	v_lshlrev_b32_e32 v94, 16, v65
	v_mul_f32_e32 v68, v95, v95
	v_lshlrev_b32_e32 v97, 16, v64
	v_lshlrev_b32_e32 v96, 16, v66
	v_pk_mul_f32 v[64:65], v[132:133], v[132:133]
	v_pk_fma_f32 v[68:69], v[94:95], v[94:95], v[68:69] op_sel_hi:[1,1,0]
	v_pk_fma_f32 v[64:65], v[96:97], v[96:97], v[64:65]
	v_lshlrev_b32_e32 v92, 16, v67
	v_pk_add_f32 v[68:69], v[64:65], v[68:69] op_sel:[1,0] op_sel_hi:[0,1]
	v_pk_add_f32 v[146:147], v[64:65], v[68:69]
	v_and_b32_e32 v93, 0xffff0000, v67
	v_mul_f32_e32 v64, v92, v92
	s_movk_i32 s0, 0x1100
	v_lshlrev_b32_e32 v84, 16, v63
	v_and_b32_e32 v85, 0xffff0000, v63
	v_lshlrev_b32_e32 v74, 16, v59
	v_and_b32_e32 v75, 0xffff0000, v59
	v_and_b32_e32 v59, 0xffff0000, v48
	v_and_b32_e32 v63, 0xffff0000, v49
	global_store_short v[80:81], v82, off offset:3584
	v_pk_fma_f32 v[148:149], v[92:93], v[92:93], v[64:65] op_sel_hi:[1,1,0]
	v_mad_i64_i32 v[64:65], s[4:5], v142, s0, v[188:189]
	v_mov_b64_e32 v[66:67], s[18:19]
	s_movk_i32 s0, 0xc0
	v_lshlrev_b32_e32 v78, 16, v62
	v_and_b32_e32 v79, 0xffff0000, v62
	v_lshlrev_b32_e32 v70, 16, v58
	v_and_b32_e32 v71, 0xffff0000, v58
	v_lshlrev_b32_e32 v76, 16, v52
	v_and_b32_e32 v77, 0xffff0000, v52
	v_lshlrev_b32_e32 v58, 16, v48
	v_lshlrev_b32_e32 v82, 16, v53
	v_and_b32_e32 v83, 0xffff0000, v53
	v_lshlrev_b32_e32 v62, 16, v49
	v_mov_b32_e32 v52, v59
	v_mov_b32_e32 v53, v63
	v_mad_u64_u32 v[68:69], s[4:5], v64, s0, v[66:67]
	v_lshlrev_b32_e32 v66, 16, v60
	v_and_b32_e32 v67, 0xffff0000, v60
	v_lshlrev_b32_e32 v72, 16, v61
	v_and_b32_e32 v73, 0xffff0000, v61
	v_lshlrev_b32_e32 v60, 16, v57
	v_and_b32_e32 v61, 0xffff0000, v57
	v_mov_b32_e32 v48, v58
	v_mov_b32_e32 v49, v62
	v_pk_mul_f32 v[52:53], v[52:53], v[52:53]
	v_and_b32_e32 v81, 0xffff0000, v50
	v_and_b32_e32 v57, 0xffff0000, v51
	v_mad_i32_i24 v69, v65, s0, v69
	v_lshlrev_b32_e32 v64, 16, v56
	v_and_b32_e32 v65, 0xffff0000, v56
	v_pk_fma_f32 v[140:141], v[48:49], v[48:49], v[52:53]
	v_lshlrev_b32_e32 v80, 16, v50
	v_cndmask_b32_e64 v53, 0, v5, s[6:7]
	v_cndmask_b32_e64 v52, 0, v4, s[6:7]
	v_lshlrev_b32_e32 v56, 16, v51
	v_mov_b32_e32 v4, v57
	v_mov_b32_e32 v5, v81
	v_cndmask_b32_e64 v49, 1.0, v1, s[6:7]
	v_cndmask_b32_e64 v48, 1.0, v0, s[6:7]
	v_mov_b32_e32 v0, v56
	v_mov_b32_e32 v1, v80
	v_pk_mul_f32 v[4:5], v[4:5], v[4:5]
	v_mov_b32_e32 v88, 0
	v_lshlrev_b32_e32 v86, 16, v54
	v_and_b32_e32 v87, 0xffff0000, v54
	v_lshlrev_b32_e32 v90, 16, v55
	v_and_b32_e32 v91, 0xffff0000, v55
	v_pk_fma_f32 v[152:153], v[0:1], v[0:1], v[4:5]
	v_cndmask_b32_e64 v51, 1.0, v3, s[6:7]
	v_cndmask_b32_e64 v50, 1.0, v2, s[6:7]
	v_cndmask_b32_e64 v55, 0, v7, s[6:7]
	v_cndmask_b32_e64 v54, 0, v6, s[6:7]
	ds_read_b128 v[0:3], v88 offset:16
	ds_read_b128 v[4:7], v88
	v_pk_mul_f32 v[160:161], v[72:73], v[72:73]
	v_pk_mul_f32 v[162:163], v[78:79], v[78:79]
	v_mov_b32_e32 v136, v160
	v_pk_mov_b32 v[44:45], v[160:161], v[134:135] op_sel:[1,0]
	v_mov_b32_e32 v144, v162
	v_pk_add_f32 v[44:45], v[136:137], v[44:45]
	v_pk_mov_b32 v[46:47], v[162:163], v[138:139] op_sel:[1,0]
	v_and_b32_e32 v137, 0xffff0000, v43
	v_pk_add_f32 v[46:47], v[144:145], v[46:47]
	v_lshlrev_b32_e32 v136, 16, v43
	v_mov_b32_e32 v144, v151
	v_mov_b32_e32 v145, v137
	v_mov_b32_e32 v138, v150
	v_mov_b32_e32 v139, v136
	v_pk_mul_f32 v[144:145], v[144:145], v[144:145]
; DI unsigned cvtpk(float lo, float hi) { f32x2_t v = {lo, hi}; bf16x2_t b = __builtin_convertvector(v, bf16x2_t); return __builtin_bit_cast(unsigned, b); }
; #define UNPK(W_, E_) const float E_[8] = {bflo((W_).x), bfhi((W_).x), bflo((W_).y), bfhi((W_).y), bflo((W_).z), bfhi((W_).z), bflo((W_).w), bfhi((W_).w)}
; #define SSQ8(W_, ACC_) do { UNPK(W_, e_); ACC_ += (e_[0] * e_[0] + e_[1] * e_[1]) + (e_[2] * e_[2] + e_[3] * e_[3]) + (e_[4] * e_[4] + e_[5] * e_[5]) + (e_[6] * e_[6] + e_[7] * e_[7]); } while (0)
; DI void phase_mla_fin(ArgsP a, int tb_, int l, char* shm, int vcu, int G) {
;     ...
; #pragma unroll
;             for (int i = 0; i < 8; ++i) SSQ8(w[i], ss);
; #pragma unroll
;             for (int i = 0; i < 4; ++i) SSQ8(krp[i], sk);
;             const float rn = rsqrtf((ss * rkv * rkv + sk) * (1.f / 96.f) + EPS);
;             u32x4* o = (u32x4*)(Kb + (bh * KVLEN + pos) * 96);
; #pragma unroll
;             for (int i = 0; i < 8; ++i) { UNPK(w[i], e); const float sc = rn * rkv; u32x4 ow;
;                 ow.x = cvtpk(e[0] * sc * gkn[8 * i], e[1] * sc * gkn[8 * i + 1]); ow.y = cvtpk(e[2] * sc * gkn[8 * i + 2], e[3] * sc * gkn[8 * i + 3]);
;                 ow.z = cvtpk(e[4] * sc * gkn[8 * i + 4], e[5] * sc * gkn[8 * i + 5]); ow.w = cvtpk(e[6] * sc * gkn[8 * i + 6], e[7] * sc * gkn[8 * i + 7]); o[i] = ow; }
	v_pk_mul_f32 v[164:165], v[84:85], v[84:85]
	v_pk_fma_f32 v[138:139], v[138:139], v[138:139], v[144:145]
	v_and_b32_e32 v145, 0xffff0000, v42
	v_pk_mov_b32 v[134:135], v[164:165], v[146:147] op_sel:[1,0]
	v_lshlrev_b32_e32 v144, 16, v42
	v_mov_b32_e32 v146, v155
	v_mov_b32_e32 v147, v145
	v_mov_b32_e32 v42, v154
	v_mov_b32_e32 v43, v144
	v_pk_mul_f32 v[146:147], v[146:147], v[146:147]
	v_mov_b32_e32 v148, v164
	v_pk_fma_f32 v[42:43], v[42:43], v[42:43], v[146:147]
	v_and_b32_e32 v147, 0xffff0000, v41
	v_lshlrev_b32_e32 v146, 16, v41
	v_mov_b32_e32 v160, v157
	v_mov_b32_e32 v161, v147
	v_pk_add_f32 v[134:135], v[148:149], v[134:135]
	v_mov_b32_e32 v148, v156
	v_mov_b32_e32 v149, v146
	v_pk_mul_f32 v[160:161], v[160:161], v[160:161]
	v_mov_b32_e32 v162, v158
	v_pk_fma_f32 v[148:149], v[148:149], v[148:149], v[160:161]
	v_and_b32_e32 v161, 0xffff0000, v40
	v_lshlrev_b32_e32 v160, 16, v40
	v_mov_b32_e32 v40, v159
	v_mov_b32_e32 v41, v161
	v_pk_mul_f32 v[40:41], v[40:41], v[40:41]
	v_mov_b32_e32 v163, v160
	v_pk_fma_f32 v[40:41], v[162:163], v[162:163], v[40:41]
	v_pk_mul_f32 v[142:143], v[66:67], v[66:67]
	v_pk_add_f32 v[40:41], v[40:41], v[148:149]
	v_mov_b32_e32 v128, v143
	v_pk_add_f32 v[40:41], v[42:43], v[40:41]
	v_mov_b32_e32 v148, v83
	v_pk_add_f32 v[40:41], v[138:139], v[40:41]
	v_mov_b32_e32 v138, v124
	v_pk_add_f32 v[40:41], v[40:41], v[40:41] op_sel_hi:[0,1]
	v_mov_b32_e32 v143, v41
	v_pk_add_f32 v[40:41], v[142:143], v[128:129]
	v_mov_b32_e32 v142, v122
	v_pk_add_f32 v[40:41], v[40:41], v[44:45]
	v_mov_b32_e32 v44, v74
	v_pk_add_f32 v[40:41], v[40:41], v[46:47]
	v_mov_b32_e32 v46, v75
	v_pk_add_f32 v[42:43], v[40:41], v[134:135]
	v_and_b32_e32 v41, 0xffff0000, v39
	v_lshlrev_b32_e32 v40, 16, v39
	v_mov_b32_e32 v47, v41
	v_mov_b32_e32 v45, v40
	v_pk_mul_f32 v[46:47], v[46:47], v[46:47]
	v_mov_b32_e32 v143, v120
	v_pk_fma_f32 v[44:45], v[44:45], v[44:45], v[46:47]
	v_and_b32_e32 v47, 0xffff0000, v38
	v_mov_b32_e32 v120, v123
	v_lshlrev_b32_e32 v46, 16, v38
	v_mov_b32_e32 v122, v71
	v_mov_b32_e32 v123, v47
	v_mov_b32_e32 v38, v70
	v_mov_b32_e32 v39, v46
	v_pk_mul_f32 v[122:123], v[122:123], v[122:123]
	v_mov_b32_e32 v128, v103
	v_pk_fma_f32 v[38:39], v[38:39], v[38:39], v[122:123]
	v_and_b32_e32 v123, 0xffff0000, v37
	v_mov_b32_e32 v129, v131
	v_mov_b32_e32 v103, v130
	v_lshlrev_b32_e32 v122, 16, v37
	v_mov_b32_e32 v130, v61
	v_mov_b32_e32 v131, v123
	v_mov_b32_e32 v134, v109
	v_mov_b32_e32 v135, v127
	v_mov_b32_e32 v109, v126
	v_mov_b32_e32 v126, v60
	v_mov_b32_e32 v127, v122
	v_pk_mul_f32 v[130:131], v[130:131], v[130:131]
	v_mov_b32_e32 v139, v110
	v_pk_fma_f32 v[130:131], v[126:127], v[126:127], v[130:131]
	v_and_b32_e32 v127, 0xffff0000, v36
	v_mov_b32_e32 v110, v125
	v_mov_b32_e32 v124, v97
	v_mov_b32_e32 v125, v133
	v_mov_b32_e32 v97, v132
	v_lshlrev_b32_e32 v126, 16, v36
	v_mov_b32_e32 v132, v65
	v_mov_b32_e32 v133, v127
	v_mov_b32_e32 v36, v64
	v_mov_b32_e32 v37, v126
	v_pk_mul_f32 v[132:133], v[132:133], v[132:133]
	v_mov_b32_e32 v162, v77
	v_pk_fma_f32 v[36:37], v[36:37], v[36:37], v[132:133]
	s_nop 0
	v_pk_add_f32 v[36:37], v[36:37], v[130:131]
	s_nop 0
	v_pk_add_f32 v[36:37], v[38:39], v[36:37]
	v_mov_b32_e32 v38, v90
	v_pk_add_f32 v[36:37], v[44:45], v[36:37]
	v_mov_b32_e32 v44, v82
	v_pk_add_f32 v[130:131], v[42:43], v[36:37]
	v_and_b32_e32 v37, 0xffff0000, v35
	v_lshlrev_b32_e32 v36, 16, v35
	v_mov_b32_e32 v42, v91
	v_mov_b32_e32 v43, v37
	v_mov_b32_e32 v39, v36
	v_pk_mul_f32 v[42:43], v[42:43], v[42:43]
	s_nop 0
	v_pk_fma_f32 v[132:133], v[38:39], v[38:39], v[42:43]
	v_and_b32_e32 v39, 0xffff0000, v34
	v_lshlrev_b32_e32 v38, 16, v34
	v_mov_b32_e32 v42, v87
	v_mov_b32_e32 v43, v39
	v_mov_b32_e32 v34, v86
	v_mov_b32_e32 v35, v38
	v_pk_mul_f32 v[42:43], v[42:43], v[42:43]
	s_nop 0
	v_pk_fma_f32 v[34:35], v[34:35], v[34:35], v[42:43]
	v_and_b32_e32 v43, 0xffff0000, v33
	v_lshlrev_b32_e32 v42, 16, v33
	v_mov_b32_e32 v149, v43
	v_mov_b32_e32 v45, v42
	v_pk_mul_f32 v[148:149], v[148:149], v[148:149]
	s_nop 0
	v_pk_fma_f32 v[148:149], v[44:45], v[44:45], v[148:149]
	v_and_b32_e32 v45, 0xffff0000, v32
	v_lshlrev_b32_e32 v44, 16, v32
	v_mov_b32_e32 v163, v45
	v_mov_b32_e32 v32, v76
	v_mov_b32_e32 v33, v44
	v_pk_mul_f32 v[162:163], v[162:163], v[162:163]
	s_nop 0
	v_pk_fma_f32 v[32:33], v[32:33], v[32:33], v[162:163]
	s_nop 0
	v_pk_add_f32 v[32:33], v[32:33], v[148:149]
	s_nop 0
	v_pk_add_f32 v[32:33], v[34:35], v[32:33]
	v_add_f32_e32 v34, v140, v141
	v_pk_add_f32 v[32:33], v[132:133], v[32:33]
	v_add_f32_e32 v34, v153, v34
	v_pk_add_f32 v[32:33], v[130:131], v[32:33]
	v_add_f32_e32 v34, v152, v34
	v_mul_f32_e32 v33, v33, v119
	v_add_f32_e32 v32, v32, v34
	v_fmac_f32_e32 v32, v119, v33
	v_fmamk_f32 v32, v32, 0x3c2aaaab, v230
	v_cmp_gt_f32_e64 s[8:9], s76, v32
	v_mul_f32_e32 v33, 0x4b800000, v32
	s_nop 0
	v_cndmask_b32_e64 v32, v32, v33, s[8:9]
	v_rsq_f32_e32 v32, v32
	s_nop 0
	v_mul_f32_e32 v33, 0x45800000, v32
	v_cndmask_b32_e64 v32, v32, v33, s[8:9]
	v_mul_f32_e32 v34, v119, v32
	v_pk_mul_f32 v[130:131], v[34:35], v[158:159] op_sel_hi:[0,1]
	s_waitcnt lgkmcnt(0)
	v_pk_mul_f32 v[4:5], v[130:131], v[4:5]
	v_pk_mul_f32 v[130:131], v[34:35], v[156:157] op_sel_hi:[0,1]
	v_pk_mul_f32 v[6:7], v[130:131], v[6:7]
	v_cvt_pk_bf16_f32 v4, v4, v5
	v_cvt_pk_bf16_f32 v5, v6, v7
	v_pk_mul_f32 v[6:7], v[34:35], v[154:155] op_sel_hi:[0,1]
	v_pk_mul_f32 v[0:1], v[6:7], v[0:1]
	v_pk_mul_f32 v[58:59], v[32:33], v[58:59] op_sel_hi:[0,1]
	v_cvt_pk_bf16_f32 v6, v0, v1
	v_pk_mul_f32 v[0:1], v[34:35], v[150:151] op_sel_hi:[0,1]
	v_pk_mul_f32 v[0:1], v[0:1], v[2:3]
	s_nop 0
	v_cvt_pk_bf16_f32 v7, v0, v1
	global_store_dwordx4 v[68:69], v[4:7], off
	s_nop 1
	ds_read_b128 v[0:3], v88 offset:32
	s_nop 0
	v_pk_mul_f32 v[4:5], v[34:35], v[160:161] op_sel_hi:[0,1]
	v_pk_mul_f32 v[6:7], v[34:35], v[144:145] op_sel_hi:[0,1]
	s_waitcnt lgkmcnt(0)
; DI unsigned cvtpk(float lo, float hi) { f32x2_t v = {lo, hi}; bf16x2_t b = __builtin_convertvector(v, bf16x2_t); return __builtin_bit_cast(unsigned, b); }
; #define UNPK(W_, E_) const float E_[8] = {bflo((W_).x), bfhi((W_).x), bflo((W_).y), bfhi((W_).y), bflo((W_).z), bfhi((W_).z), bflo((W_).w), bfhi((W_).w)}
; DI void phase_mla_fin(ArgsP a, int tb_, int l, char* shm, int vcu, int G) {
;     ...
;             u32x4* o = (u32x4*)(Kb + (bh * KVLEN + pos) * 96);
; #pragma unroll
;             for (int i = 0; i < 8; ++i) { UNPK(w[i], e); const float sc = rn * rkv; u32x4 ow;
;                 ow.x = cvtpk(e[0] * sc * gkn[8 * i], e[1] * sc * gkn[8 * i + 1]); ow.y = cvtpk(e[2] * sc * gkn[8 * i + 2], e[3] * sc * gkn[8 * i + 3]);
;                 ow.z = cvtpk(e[4] * sc * gkn[8 * i + 4], e[5] * sc * gkn[8 * i + 5]); ow.w = cvtpk(e[6] * sc * gkn[8 * i + 6], e[7] * sc * gkn[8 * i + 7]); o[i] = ow; }
;             float cs[16], sn[16];
; #pragma unroll
;             for (int i = 0; i < 4; ++i) { cs[4 * i] = lat ? rc[i].x : 1.f; cs[4 * i + 1] = lat ? rc[i].y : 1.f; cs[4 * i + 2] = lat ? rc[i].z : 1.f; cs[4 * i + 3] = lat ? rc[i].w : 1.f;
;                 sn[4 * i] = lat ? rs[i].x : 0.f; sn[4 * i + 1] = lat ? rs[i].y : 0.f; sn[4 * i + 2] = lat ? rs[i].z : 0.f; sn[4 * i + 3] = lat ? rs[i].w : 0.f; }
;             float xr[32];
; #pragma unroll
;             for (int i = 0; i < 4; ++i) { UNPK(krp[i], e);
; #pragma unroll
;                 for (int j = 0; j < 8; ++j) xr[8 * i + j] = e[j] * rn * gkn[64 + 8 * i + j]; }
	v_pk_mul_f32 v[0:1], v[4:5], v[0:1]
	v_pk_mul_f32 v[4:5], v[34:35], v[146:147] op_sel_hi:[0,1]
	v_pk_mul_f32 v[2:3], v[4:5], v[2:3]
	v_cvt_pk_bf16_f32 v0, v0, v1
	v_cvt_pk_bf16_f32 v1, v2, v3
	ds_read_b128 v[2:5], v88 offset:48
	s_waitcnt lgkmcnt(0)
	v_pk_mul_f32 v[2:3], v[6:7], v[2:3]
	v_pk_mul_f32 v[6:7], v[34:35], v[136:137] op_sel_hi:[0,1]
	v_pk_mul_f32 v[4:5], v[6:7], v[4:5]
	v_cvt_pk_bf16_f32 v2, v2, v3
	v_cvt_pk_bf16_f32 v3, v4, v5
	global_store_dwordx4 v[68:69], v[0:3], off offset:16
	s_nop 1
	ds_read_b128 v[0:3], v88 offset:64
	v_pk_mul_f32 v[4:5], v[34:35], v[142:143] op_sel_hi:[0,1]
	v_pk_mul_f32 v[6:7], v[34:35], v[138:139] op_sel_hi:[0,1]
	s_waitcnt lgkmcnt(0)
	v_pk_mul_f32 v[0:1], v[4:5], v[0:1]
	v_pk_mul_f32 v[4:5], v[34:35], v[120:121] op_sel_hi:[0,1]
	v_pk_mul_f32 v[2:3], v[4:5], v[2:3]
	v_cvt_pk_bf16_f32 v0, v0, v1
	v_cvt_pk_bf16_f32 v1, v2, v3
	ds_read_b128 v[2:5], v88 offset:80
	s_waitcnt lgkmcnt(0)
	v_pk_mul_f32 v[2:3], v[6:7], v[2:3]
	v_pk_mul_f32 v[6:7], v[34:35], v[110:111] op_sel_hi:[0,1]
	v_pk_mul_f32 v[4:5], v[6:7], v[4:5]
	v_cvt_pk_bf16_f32 v2, v2, v3
	v_cvt_pk_bf16_f32 v3, v4, v5
	global_store_dwordx4 v[68:69], v[0:3], off offset:32
	s_nop 1
	ds_read_b128 v[0:3], v88 offset:96
	v_pk_mul_f32 v[4:5], v[34:35], v[134:135] op_sel_hi:[0,1]
	v_pk_mul_f32 v[6:7], v[34:35], v[108:109] op_sel_hi:[0,1]
	s_waitcnt lgkmcnt(0)
	v_pk_mul_f32 v[0:1], v[4:5], v[0:1]
	v_pk_mul_f32 v[4:5], v[34:35], v[106:107] op_sel_hi:[0,1]
	v_pk_mul_f32 v[2:3], v[4:5], v[2:3]
	v_cvt_pk_bf16_f32 v0, v0, v1
	v_cvt_pk_bf16_f32 v1, v2, v3
	ds_read_b128 v[2:5], v88 offset:112
	s_waitcnt lgkmcnt(0)
	v_pk_mul_f32 v[2:3], v[6:7], v[2:3]
	v_pk_mul_f32 v[6:7], v[34:35], v[104:105] op_sel_hi:[0,1]
	v_pk_mul_f32 v[4:5], v[6:7], v[4:5]
	v_cvt_pk_bf16_f32 v2, v2, v3
	v_cvt_pk_bf16_f32 v3, v4, v5
	global_store_dwordx4 v[68:69], v[0:3], off offset:48
	s_nop 1
	ds_read_b128 v[0:3], v88 offset:128
	v_pk_mul_f32 v[4:5], v[34:35], v[128:129] op_sel_hi:[0,1]
	v_pk_mul_f32 v[6:7], v[34:35], v[102:103] op_sel_hi:[0,1]
	s_waitcnt lgkmcnt(0)
	v_pk_mul_f32 v[0:1], v[4:5], v[0:1]
	v_pk_mul_f32 v[4:5], v[34:35], v[100:101] op_sel_hi:[0,1]
	v_pk_mul_f32 v[2:3], v[4:5], v[2:3]
	v_cvt_pk_bf16_f32 v0, v0, v1
	v_cvt_pk_bf16_f32 v1, v2, v3
	ds_read_b128 v[2:5], v88 offset:144
	s_waitcnt lgkmcnt(0)
	v_pk_mul_f32 v[2:3], v[6:7], v[2:3]
	v_pk_mul_f32 v[6:7], v[34:35], v[98:99] op_sel_hi:[0,1]
	v_pk_mul_f32 v[4:5], v[6:7], v[4:5]
	v_cvt_pk_bf16_f32 v2, v2, v3
	v_cvt_pk_bf16_f32 v3, v4, v5
	global_store_dwordx4 v[68:69], v[0:3], off offset:64
	s_nop 1
	ds_read_b128 v[0:3], v88 offset:160
	v_pk_mul_f32 v[4:5], v[34:35], v[124:125] op_sel_hi:[0,1]
	v_pk_mul_f32 v[6:7], v[34:35], v[96:97] op_sel_hi:[0,1]
	s_waitcnt lgkmcnt(0)
	v_pk_mul_f32 v[0:1], v[4:5], v[0:1]
	v_pk_mul_f32 v[4:5], v[34:35], v[94:95] op_sel_hi:[0,1]
	v_pk_mul_f32 v[2:3], v[4:5], v[2:3]
	v_cvt_pk_bf16_f32 v0, v0, v1
	v_cvt_pk_bf16_f32 v1, v2, v3
	ds_read_b128 v[2:5], v88 offset:176
	s_waitcnt lgkmcnt(0)
	v_pk_mul_f32 v[2:3], v[6:7], v[2:3]
	v_pk_mul_f32 v[6:7], v[34:35], v[92:93] op_sel_hi:[0,1]
	v_pk_mul_f32 v[4:5], v[6:7], v[4:5]
	v_cvt_pk_bf16_f32 v2, v2, v3
	v_cvt_pk_bf16_f32 v3, v4, v5
	global_store_dwordx4 v[68:69], v[0:3], off offset:80
	s_nop 1
	ds_read_b128 v[0:3], v88 offset:192
	v_pk_mul_f32 v[4:5], v[34:35], v[126:127] op_sel_hi:[0,1]
	v_pk_mul_f32 v[6:7], v[34:35], v[46:47] op_sel_hi:[0,1]
	s_waitcnt lgkmcnt(0)
	v_pk_mul_f32 v[0:1], v[4:5], v[0:1]
	v_pk_mul_f32 v[4:5], v[34:35], v[122:123] op_sel_hi:[0,1]
	v_pk_mul_f32 v[2:3], v[4:5], v[2:3]
	v_cvt_pk_bf16_f32 v0, v0, v1
	v_cvt_pk_bf16_f32 v1, v2, v3
	ds_read_b128 v[2:5], v88 offset:208
	s_waitcnt lgkmcnt(0)
	v_pk_mul_f32 v[2:3], v[6:7], v[2:3]
	v_pk_mul_f32 v[6:7], v[34:35], v[40:41] op_sel_hi:[0,1]
	v_pk_mul_f32 v[4:5], v[6:7], v[4:5]
	v_cvt_pk_bf16_f32 v2, v2, v3
	v_cvt_pk_bf16_f32 v3, v4, v5
	global_store_dwordx4 v[68:69], v[0:3], off offset:96
	s_nop 1
	ds_read_b128 v[0:3], v88 offset:224
	v_pk_mul_f32 v[4:5], v[34:35], v[44:45] op_sel_hi:[0,1]
	v_pk_mul_f32 v[6:7], v[34:35], v[38:39] op_sel_hi:[0,1]
	s_waitcnt lgkmcnt(0)
	v_pk_mul_f32 v[0:1], v[4:5], v[0:1]
	v_pk_mul_f32 v[4:5], v[34:35], v[42:43] op_sel_hi:[0,1]
	v_pk_mul_f32 v[2:3], v[4:5], v[2:3]
	v_cvt_pk_bf16_f32 v0, v0, v1
	v_cvt_pk_bf16_f32 v1, v2, v3
	ds_read_b128 v[2:5], v88 offset:240
	s_waitcnt lgkmcnt(0)
	v_pk_mul_f32 v[2:3], v[6:7], v[2:3]
	v_pk_mul_f32 v[6:7], v[34:35], v[36:37] op_sel_hi:[0,1]
	v_pk_mul_f32 v[4:5], v[6:7], v[4:5]
	v_cvt_pk_bf16_f32 v2, v2, v3
	v_cvt_pk_bf16_f32 v3, v4, v5
	global_store_dwordx4 v[68:69], v[0:3], off offset:112
	s_nop 1
	ds_read_b128 v[2:5], v88 offset:256
	s_nop 0
	ds_read_b128 v[34:37], v88 offset:272
	v_pk_mul_f32 v[0:1], v[32:33], v[66:67] op_sel_hi:[0,1]
	ds_read_b128 v[40:43], v88 offset:304
	ds_read_b128 v[44:47], v88 offset:320
	s_waitcnt lgkmcnt(0)
	v_pk_mul_f32 v[2:3], v[0:1], v[2:3]
	v_pk_mul_f32 v[0:1], v[32:33], v[72:73] op_sel_hi:[0,1]
	v_pk_mul_f32 v[0:1], v[0:1], v[4:5]
	v_pk_mul_f32 v[4:5], v[32:33], v[78:79] op_sel_hi:[0,1]
	v_pk_mul_f32 v[6:7], v[4:5], v[34:35]
	v_pk_mul_f32 v[4:5], v[32:33], v[84:85] op_sel_hi:[0,1]
	v_pk_mul_f32 v[4:5], v[4:5], v[36:37]
	ds_read_b128 v[36:39], v88 offset:288
	v_pk_mul_f32 v[34:35], v[32:33], v[64:65] op_sel_hi:[0,1]
	ds_read_b128 v[64:67], v88 offset:336
	s_waitcnt lgkmcnt(0)
; #define UNPK(W_, E_) const float E_[8] = {bflo((W_).x), bfhi((W_).x), bflo((W_).y), bfhi((W_).y), bflo((W_).z), bfhi((W_).z), bflo((W_).w), bfhi((W_).w)}
; #define SSQ8(W_, ACC_) do { UNPK(W_, e_); ACC_ += (e_[0] * e_[0] + e_[1] * e_[1]) + (e_[2] * e_[2] + e_[3] * e_[3]) + (e_[4] * e_[4] + e_[5] * e_[5]) + (e_[6] * e_[6] + e_[7] * e_[7]); } while (0)
; #define ROPE32(xr) _Pragma("unroll") for (int ax = 0; ax < 2; ++ax) _Pragma("unroll") for (int f = 0; f < 8; ++f) { const float x1 = xr[16 * ax + f], x2 = xr[16 * ax + 8 + f], c = cs[8 * ax + f], sv = sn[8 * ax + f]; xr[16 * ax + f] = x1 * c - x2 * sv; xr[16 * ax + 8 + f] = x2 * c + x1 * sv; }
; DI void phase_mla_fin(ArgsP a, int tb_, int l, char* shm, int vcu, int G) {
;     ...
;             const u32x4* ps = (const u32x4*)(zcq + (size_t)m * 256) + 4 * h; const u32x4* p = (const u32x4*)(qraw + (size_t)m * 768 + h * 96);
;             u32x4 st[4], w[12];
; #pragma unroll
;             for (int i = 0; i < 4; ++i) st[i] = ps[i];
; #pragma unroll
;             for (int i = 0; i < 12; ++i) w[i] = p[i];
;             const float* gqn = gqn0; asm volatile("" : "+s"(gqn));
;             float cs[16], sn[16];
; #pragma unroll
;             for (int i = 0; i < 4; ++i) { cs[4 * i] = lat ? rc[i].x : 1.f; cs[4 * i + 1] = lat ? rc[i].y : 1.f; cs[4 * i + 2] = lat ? rc[i].z : 1.f; cs[4 * i + 3] = lat ? rc[i].w : 1.f;
;                 sn[4 * i] = lat ? rs[i].x : 0.f; sn[4 * i + 1] = lat ? rs[i].y : 0.f; sn[4 * i + 2] = lat ? rs[i].z : 0.f; sn[4 * i + 3] = lat ? rs[i].w : 0.f; }
;             float ssq = 0.f, ss = 0.f;
; #pragma unroll
;             for (int i = 0; i < 4; ++i) SSQ8(st[i], ssq);
;     ...
;             for (int i = 0; i < 4; ++i) { UNPK(krp[i], e);
; #pragma unroll
;                 for (int j = 0; j < 8; ++j) xr[8 * i + j] = e[j] * rn * gkn[64 + 8 * i + j]; }
;             ROPE32(xr)
	v_pk_mul_f32 v[36:37], v[34:35], v[36:37]
	v_pk_mul_f32 v[34:35], v[32:33], v[60:61] op_sel_hi:[0,1]
	v_pk_mul_f32 v[34:35], v[34:35], v[38:39]
	v_pk_mul_f32 v[38:39], v[32:33], v[70:71] op_sel_hi:[0,1]
	ds_read_b128 v[70:73], v88 offset:352
	v_pk_mul_f32 v[40:41], v[38:39], v[40:41]
	v_pk_mul_f32 v[38:39], v[32:33], v[74:75] op_sel_hi:[0,1]
	v_pk_mul_f32 v[38:39], v[38:39], v[42:43]
	v_pk_mul_f32 v[42:43], v[32:33], v[76:77] op_sel_hi:[0,1]
	v_pk_mul_f32 v[44:45], v[42:43], v[44:45]
	v_pk_mul_f32 v[42:43], v[32:33], v[82:83] op_sel_hi:[0,1]
	v_pk_mul_f32 v[42:43], v[42:43], v[46:47]
	v_pk_mul_f32 v[46:47], v[32:33], v[86:87] op_sel_hi:[0,1]
	v_pk_mul_f32 v[60:61], v[46:47], v[64:65]
	v_pk_mul_f32 v[46:47], v[32:33], v[90:91] op_sel_hi:[0,1]
	v_pk_mul_f32 v[46:47], v[46:47], v[66:67]
	s_waitcnt lgkmcnt(0)
	v_pk_mul_f32 v[66:67], v[58:59], v[70:71]
	v_pk_mul_f32 v[58:59], v[32:33], v[62:63] op_sel_hi:[0,1]
	v_pk_mul_f32 v[62:63], v[58:59], v[72:73]
	ds_read_b128 v[70:73], v88 offset:368
	v_pk_mul_f32 v[58:59], v[32:33], v[80:81] op_sel_hi:[0,1]
	v_pk_mul_f32 v[32:33], v[32:33], v[56:57] op_sel_hi:[0,1]
	s_waitcnt lgkmcnt(0)
	v_pk_mul_f32 v[56:57], v[32:33], v[72:73]
	v_pk_mul_f32 v[32:33], v[24:25], v[36:37]
	v_pk_mul_f32 v[36:37], v[28:29], v[36:37]
	v_pk_mul_f32 v[70:71], v[58:59], v[70:71]
	v_pk_fma_f32 v[58:59], v[24:25], v[2:3], v[36:37] neg_lo:[0,0,1] neg_hi:[0,0,1]
	v_pk_fma_f32 v[64:65], v[28:29], v[2:3], v[32:33]
	v_pk_mul_f32 v[2:3], v[26:27], v[34:35]
	v_pk_mul_f32 v[24:25], v[30:31], v[34:35]
	v_pk_fma_f32 v[74:75], v[30:31], v[0:1], v[2:3]
	v_pk_fma_f32 v[34:35], v[26:27], v[0:1], v[24:25] neg_lo:[0,0,1] neg_hi:[0,0,1]
	v_pk_mul_f32 v[0:1], v[16:17], v[40:41]
	v_pk_mul_f32 v[2:3], v[20:21], v[40:41]
	v_pk_fma_f32 v[78:79], v[20:21], v[6:7], v[0:1]
	v_pk_fma_f32 v[76:77], v[16:17], v[6:7], v[2:3] neg_lo:[0,0,1] neg_hi:[0,0,1]
	v_pk_mul_f32 v[0:1], v[18:19], v[38:39]
	v_pk_mul_f32 v[2:3], v[22:23], v[38:39]
	v_pk_fma_f32 v[80:81], v[22:23], v[4:5], v[0:1]
	v_pk_fma_f32 v[38:39], v[18:19], v[4:5], v[2:3] neg_lo:[0,0,1] neg_hi:[0,0,1]
	v_pk_mul_f32 v[0:1], v[8:9], v[66:67]
	v_pk_mul_f32 v[2:3], v[12:13], v[66:67]
	v_pk_fma_f32 v[66:67], v[12:13], v[44:45], v[0:1]
	v_pk_fma_f32 v[36:37], v[8:9], v[44:45], v[2:3] neg_lo:[0,0,1] neg_hi:[0,0,1]
	v_pk_mul_f32 v[0:1], v[10:11], v[62:63]
	v_pk_mul_f32 v[2:3], v[14:15], v[62:63]
	s_nop 0
	v_pk_fma_f32 v[32:33], v[10:11], v[42:43], v[2:3] neg_lo:[0,0,1] neg_hi:[0,0,1]
	v_pk_fma_f32 v[42:43], v[14:15], v[42:43], v[0:1]
	v_pk_mul_f32 v[0:1], v[48:49], v[70:71]
	v_pk_mul_f32 v[2:3], v[52:53], v[70:71]
	s_nop 0
	v_pk_fma_f32 v[44:45], v[48:49], v[60:61], v[2:3] neg_lo:[0,0,1] neg_hi:[0,0,1]
	v_pk_fma_f32 v[48:49], v[52:53], v[60:61], v[0:1]
	v_pk_mul_f32 v[0:1], v[50:51], v[56:57]
	v_pk_mul_f32 v[2:3], v[54:55], v[56:57]
	v_pk_fma_f32 v[40:41], v[54:55], v[46:47], v[0:1]
	v_pk_fma_f32 v[50:51], v[50:51], v[46:47], v[2:3] neg_lo:[0,0,1] neg_hi:[0,0,1]
.LBB0_967:
	s_andn2_saveexec_b64 s[30:31], s[30:31]
	s_cbranch_execz .LBB0_964
	v_lshl_add_u64 v[32:33], v[114:115], 0, v[52:53]
	global_load_dwordx4 v[80:83], v[32:33], off offset:48
	global_load_dwordx4 v[84:87], v[32:33], off offset:32
	global_load_dwordx4 v[90:93], v[32:33], off offset:16
	global_load_dwordx4 v[94:97], v[32:33], off
	s_movk_i32 s0, 0x600
	v_mad_i64_i32 v[64:65], s[4:5], v46, s0, v[116:117]
	global_load_dwordx4 v[40:43], v[64:65], off offset:16
	global_load_dwordx4 v[48:51], v[64:65], off
	global_load_dwordx4 v[72:75], v[64:65], off offset:48
	global_load_dwordx4 v[76:79], v[64:65], off offset:32
	global_load_dwordx4 v[32:35], v[64:65], off offset:112
	global_load_dwordx4 v[36:39], v[64:65], off offset:80
	global_load_dwordx4 v[44:47], v[64:65], off offset:64
	global_load_dwordx4 v[68:71], v[64:65], off offset:96
	global_load_dwordx4 v[56:59], v[64:65], off offset:160
	global_load_dwordx4 v[52:55], v[64:65], off offset:176
	global_load_dwordx4 v[60:63], v[64:65], off offset:144
	s_nop 0
	global_load_dwordx4 v[64:67], v[64:65], off offset:128
	s_movk_i32 s0, 0x1100
	s_mov_b64 s[34:35], s[22:23]
	s_waitcnt vmcnt(0)
	v_cndmask_b32_e64 v25, 1.0, v25, s[6:7]
	v_cndmask_b32_e64 v24, 1.0, v24, s[6:7]
	v_cndmask_b32_e64 v29, 0, v29, s[6:7]
	v_cndmask_b32_e64 v28, 0, v28, s[6:7]
	v_cndmask_b32_e64 v27, 1.0, v27, s[6:7]
	v_cndmask_b32_e64 v26, 1.0, v26, s[6:7]
	v_cndmask_b32_e64 v31, 0, v31, s[6:7]
	v_cndmask_b32_e64 v30, 0, v30, s[6:7]
	v_cndmask_b32_e64 v17, 1.0, v17, s[6:7]
	v_cndmask_b32_e64 v16, 1.0, v16, s[6:7]
	v_cndmask_b32_e64 v21, 0, v21, s[6:7]
	v_cndmask_b32_e64 v20, 0, v20, s[6:7]
	v_cndmask_b32_e64 v19, 1.0, v19, s[6:7]
	v_cndmask_b32_e64 v18, 1.0, v18, s[6:7]
	v_cndmask_b32_e64 v23, 0, v23, s[6:7]
	v_cndmask_b32_e64 v22, 0, v22, s[6:7]
	v_cndmask_b32_e64 v9, 1.0, v9, s[6:7]
	v_cndmask_b32_e64 v8, 1.0, v8, s[6:7]
	v_cndmask_b32_e64 v13, 0, v13, s[6:7]
	v_cndmask_b32_e64 v12, 0, v12, s[6:7]
	v_and_b32_e32 v193, 0xffff0000, v40
	v_lshlrev_b32_e32 v150, 16, v51
	v_and_b32_e32 v109, 0xffff0000, v73
	v_and_b32_e32 v108, 0xffff0000, v72
	v_and_b32_e32 v101, 0xffff0000, v80
	v_and_b32_e32 v100, 0xffff0000, v83
	v_mul_f32_e32 v106, v100, v100
	v_and_b32_e32 v89, 0xffff0000, v95
	v_lshlrev_b32_e32 v88, 16, v95
	v_mul_f32_e32 v98, v89, v89
	v_pk_fma_f32 v[88:89], v[88:89], v[88:89], v[98:99] op_sel_hi:[1,1,0]
	v_lshlrev_b32_e32 v99, 16, v94
	v_and_b32_e32 v95, 0xffff0000, v94
	v_and_b32_e32 v94, 0xffff0000, v96
	v_lshlrev_b32_e32 v98, 16, v96
	v_pk_mul_f32 v[94:95], v[94:95], v[94:95]
	v_lshlrev_b32_e32 v96, 16, v90
	v_pk_fma_f32 v[94:95], v[98:99], v[98:99], v[94:95]
	v_and_b32_e32 v90, 0xffff0000, v90
; DI float shx(float v, int mask, int lane) { return __int_as_float(__builtin_amdgcn_ds_bpermute((lane ^ mask) << 2, __float_as_int(v))); }
; #define SSQ8(W_, ACC_) do { UNPK(W_, e_); ACC_ += (e_[0] * e_[0] + e_[1] * e_[1]) + (e_[2] * e_[2] + e_[3] * e_[3]) + (e_[4] * e_[4] + e_[5] * e_[5]) + (e_[6] * e_[6] + e_[7] * e_[7]); } while (0)
; DI void phase_mla_fin(ArgsP a, int tb_, int l, char* shm, int vcu, int G) {
;     ...
;             float ssq = 0.f, ss = 0.f;
; #pragma unroll
;             for (int i = 0; i < 4; ++i) SSQ8(st[i], ssq);
;             ssq += shx(ssq, 1, lane); ssq += shx(ssq, 2, lane); ssq += shx(ssq, 4, lane);
;             const float rq = rsqrtf(ssq * (1.f / 256.f) + EPS);
; #pragma unroll
;             for (int i = 0; i < 12; ++i) SSQ8(w[i], ss);
;             const float rn = rsqrtf(ss * rq * rq * (1.f / 96.f) + EPS) * rq;
;             u32x4* o = (u32x4*)(Qb + (bh * KVLEN + pos) * 96);
	v_pk_add_f32 v[88:89], v[94:95], v[88:89] op_sel:[1,0] op_sel_hi:[0,1]
	v_pk_add_f32 v[88:89], v[94:95], v[88:89]
	v_lshlrev_b32_e32 v94, 16, v97
	v_and_b32_e32 v95, 0xffff0000, v97
	v_lshlrev_b32_e32 v97, 16, v91
	v_and_b32_e32 v91, 0xffff0000, v91
	v_pk_mul_f32 v[90:91], v[90:91], v[90:91]
	v_and_b32_e32 v99, 0xffff0000, v81
	v_pk_fma_f32 v[90:91], v[96:97], v[96:97], v[90:91]
	v_lshlrev_b32_e32 v98, 16, v81
	v_pk_add_f32 v[96:97], v[90:91], v[90:91] op_sel:[0,1] op_sel_hi:[1,0]
	v_lshlrev_b32_e32 v91, 16, v93
	v_lshlrev_b32_e32 v90, 16, v92
	v_and_b32_e32 v93, 0xffff0000, v93
	v_and_b32_e32 v92, 0xffff0000, v92
	v_pk_mul_f32 v[92:93], v[92:93], v[92:93]
	v_lshlrev_b32_e32 v81, 16, v83
	v_pk_fma_f32 v[90:91], v[90:91], v[90:91], v[92:93]
	v_mul_f32_e32 v105, v99, v99
	v_pk_add_f32 v[92:93], v[90:91], v[96:97]
	v_and_b32_e32 v97, 0xffff0000, v84
	v_lshlrev_b32_e32 v96, 16, v84
	v_lshlrev_b32_e32 v84, 16, v85
	v_and_b32_e32 v85, 0xffff0000, v85
	v_lshlrev_b32_e32 v99, 16, v80
	v_mul_f32_e32 v80, v97, v97
	v_pk_fma_f32 v[96:97], v[96:97], v[96:97], v[80:81] op_sel_hi:[1,1,0]
	v_mul_f32_e32 v80, v85, v85
	v_mul_f32_e32 v104, v98, v98
	v_and_b32_e32 v100, 0xffff0000, v86
	v_pk_mov_b32 v[102:103], v[86:87], v[82:83] op_sel:[1,0]
	v_pk_fma_f32 v[84:85], v[84:85], v[84:85], v[80:81] op_sel_hi:[1,1,0]
	v_lshlrev_b32_e32 v98, 16, v86
	v_lshlrev_b32_e32 v83, 16, v82
	v_lshlrev_b32_e32 v82, 16, v87
	v_and_b32_e32 v87, 0xffff0000, v103
	v_and_b32_e32 v86, 0xffff0000, v102
	v_pk_mul_f32 v[100:101], v[100:101], v[100:101]
	v_mov_b32_e32 v97, v104
	v_mov_b32_e32 v85, v105
	v_pk_fma_f32 v[98:99], v[98:99], v[98:99], v[100:101]
	v_pk_add_f32 v[84:85], v[96:97], v[84:85]
	v_pk_mul_f32 v[86:87], v[86:87], v[86:87]
	v_pk_add_f32 v[84:85], v[98:99], v[84:85]
	v_pk_fma_f32 v[82:83], v[82:83], v[82:83], v[86:87]
	v_mul_f32_e32 v80, v95, v95
	v_pk_add_f32 v[82:83], v[82:83], v[84:85]
	v_pk_fma_f32 v[84:85], v[94:95], v[94:95], v[80:81] op_sel_hi:[1,1,0]
	v_mov_b32_e32 v86, v88
	v_mov_b32_e32 v80, v84
	v_mov_b32_e32 v87, v81
	v_pk_add_f32 v[84:85], v[84:85], v[88:89]
	v_pk_mul_f32 v[80:81], v[80:81], v[86:87]
	v_and_b32_e32 v105, 0xffff0000, v44
	v_mov_b32_e32 v85, v81
	v_pk_add_f32 v[80:81], v[90:91], v[92:93] op_sel:[1,0] op_sel_hi:[0,1]
	v_mov_b32_e32 v81, v106
	v_pk_add_f32 v[80:81], v[84:85], v[80:81]
	v_lshlrev_b32_e32 v104, 16, v44
	v_pk_add_f32 v[80:81], v[80:81], v[82:83]
	v_mul_f32_e32 v44, v105, v105
	v_add_f32_e32 v80, v80, v81
	v_and_b32_e32 v101, 0xffff0000, v45
	v_pk_fma_f32 v[126:127], v[104:105], v[104:105], v[44:45] op_sel_hi:[1,1,0]
	v_lshlrev_b32_e32 v100, 16, v45
	v_mul_f32_e32 v44, v101, v101
	s_waitcnt lgkmcnt(0)
	s_nop 1
	v_add_f32_dpp v80, v80, v80 quad_perm:[1,0,3,2] row_mask:0xf bank_mask:0xf
	v_and_b32_e32 v99, 0xffff0000, v69
	v_and_b32_e32 v98, 0xffff0000, v68
	v_pk_fma_f32 v[132:133], v[100:101], v[100:101], v[44:45] op_sel_hi:[1,1,0]
	v_lshlrev_b32_e32 v125, 16, v69
	s_waitcnt lgkmcnt(0)
	s_nop 1
	v_add_f32_dpp v80, v80, v80 quad_perm:[2,3,0,1] row_mask:0xf bank_mask:0xf
	v_lshlrev_b32_e32 v124, 16, v68
	v_pk_mul_f32 v[44:45], v[98:99], v[98:99]
	v_and_b32_e32 v93, 0xffff0000, v71
	v_and_b32_e32 v92, 0xffff0000, v70
	s_waitcnt lgkmcnt(0)
	s_nop 1
	v_add_f32_dpp v80, v80, v80 row_half_mirror row_mask:0xf bank_mask:0xf
	v_fmamk_f32 v80, v80, 0x3b800000, v230
	v_lshlrev_b32_e32 v139, 16, v73
	v_lshlrev_b32_e32 v138, 16, v72
	v_pk_mul_f32 v[72:73], v[108:109], v[108:109]
	v_and_b32_e32 v103, 0xffff0000, v75
	v_and_b32_e32 v102, 0xffff0000, v74
	v_pk_fma_f32 v[44:45], v[124:125], v[124:125], v[44:45]
	v_lshlrev_b32_e32 v129, 16, v71
	v_lshlrev_b32_e32 v128, 16, v70
	v_pk_mul_f32 v[68:69], v[92:93], v[92:93]
	v_and_b32_e32 v87, 0xffff0000, v32
	v_cmp_gt_f32_e64 s[8:9], s76, v80
	v_mul_f32_e32 v81, 0x4b800000, v80
	v_pk_fma_f32 v[72:73], v[138:139], v[138:139], v[72:73]
	v_lshlrev_b32_e32 v141, 16, v75
	v_lshlrev_b32_e32 v140, 16, v74
	v_pk_mul_f32 v[74:75], v[102:103], v[102:103]
	v_pk_add_f32 v[44:45], v[44:45], v[44:45] op_sel:[0,1] op_sel_hi:[1,0]
	v_pk_fma_f32 v[68:69], v[128:129], v[128:129], v[68:69]
	v_lshlrev_b32_e32 v86, 16, v32
	v_mul_f32_e32 v32, v87, v87
	v_and_b32_e32 v85, 0xffff0000, v33
	v_cndmask_b32_e64 v80, v80, v81, s[8:9]
	v_pk_add_f32 v[72:73], v[72:73], v[72:73] op_sel:[0,1] op_sel_hi:[1,0]
	v_pk_fma_f32 v[74:75], v[140:141], v[140:141], v[74:75]
	v_pk_add_f32 v[44:45], v[68:69], v[44:45]
	v_pk_fma_f32 v[144:145], v[86:87], v[86:87], v[32:33] op_sel_hi:[1,1,0]
	v_lshlrev_b32_e32 v84, 16, v33
	v_mul_f32_e32 v32, v85, v85
	v_rsq_f32_e32 v80, v80
	v_pk_add_f32 v[72:73], v[74:75], v[72:73]
	v_pk_add_f32 v[136:137], v[68:69], v[44:45] op_sel:[1,0] op_sel_hi:[0,1]
	v_pk_fma_f32 v[148:149], v[84:85], v[84:85], v[32:33] op_sel_hi:[1,1,0]
	v_mad_i64_i32 v[32:33], s[4:5], v142, s0, v[188:189]
	v_mov_b64_e32 v[44:45], s[16:17]
	s_movk_i32 s0, 0xc0
	v_lshlrev_b32_e32 v70, 16, v60
	v_and_b32_e32 v71, 0xffff0000, v60
	v_lshlrev_b32_e32 v60, 16, v61
	v_and_b32_e32 v61, 0xffff0000, v61
	v_pk_add_f32 v[130:131], v[74:75], v[72:73] op_sel:[1,0] op_sel_hi:[0,1]
	v_mad_u64_u32 v[68:69], s[4:5], v32, s0, v[44:45]
	v_mov_b32_e32 v44, v71
	v_mov_b32_e32 v45, v61
	v_and_b32_e32 v73, 0xffff0000, v62
	v_lshlrev_b32_e32 v90, 16, v67
	v_and_b32_e32 v91, 0xffff0000, v67
	v_and_b32_e32 v67, 0xffff0000, v63
	v_mad_i32_i24 v69, v33, s0, v69
	v_mov_b32_e32 v32, v70
	v_mov_b32_e32 v33, v60
	v_pk_mul_f32 v[44:45], v[44:45], v[44:45]
	v_lshlrev_b32_e32 v88, 16, v66
	v_and_b32_e32 v89, 0xffff0000, v66
	v_lshlrev_b32_e32 v72, 16, v62
	v_lshlrev_b32_e32 v66, 16, v63
	v_mov_b32_e32 v62, v67
	v_mov_b32_e32 v63, v73
	v_and_b32_e32 v111, 0xffff0000, v77
; DI unsigned cvtpk(float lo, float hi) { f32x2_t v = {lo, hi}; bf16x2_t b = __builtin_convertvector(v, bf16x2_t); return __builtin_bit_cast(unsigned, b); }
; DI float shx(float v, int mask, int lane) { return __int_as_float(__builtin_amdgcn_ds_bpermute((lane ^ mask) << 2, __float_as_int(v))); }
; #define UNPK(W_, E_) const float E_[8] = {bflo((W_).x), bfhi((W_).x), bflo((W_).y), bfhi((W_).y), bflo((W_).z), bfhi((W_).z), bflo((W_).w), bfhi((W_).w)}
; #define SSQ8(W_, ACC_) do { UNPK(W_, e_); ACC_ += (e_[0] * e_[0] + e_[1] * e_[1]) + (e_[2] * e_[2] + e_[3] * e_[3]) + (e_[4] * e_[4] + e_[5] * e_[5]) + (e_[6] * e_[6] + e_[7] * e_[7]); } while (0)
; DI void phase_mla_fin(ArgsP a, int tb_, int l, char* shm, int vcu, int G) {
;     ...
;             float cs[16], sn[16];
; #pragma unroll
;             for (int i = 0; i < 4; ++i) { cs[4 * i] = lat ? rc[i].x : 1.f; cs[4 * i + 1] = lat ? rc[i].y : 1.f; cs[4 * i + 2] = lat ? rc[i].z : 1.f; cs[4 * i + 3] = lat ? rc[i].w : 1.f;
;                 sn[4 * i] = lat ? rs[i].x : 0.f; sn[4 * i + 1] = lat ? rs[i].y : 0.f; sn[4 * i + 2] = lat ? rs[i].z : 0.f; sn[4 * i + 3] = lat ? rs[i].w : 0.f; }
;             float ssq = 0.f, ss = 0.f;
; #pragma unroll
;             for (int i = 0; i < 4; ++i) SSQ8(st[i], ssq);
;             ssq += shx(ssq, 1, lane); ssq += shx(ssq, 2, lane); ssq += shx(ssq, 4, lane);
;             const float rq = rsqrtf(ssq * (1.f / 256.f) + EPS);
; #pragma unroll
;             for (int i = 0; i < 12; ++i) SSQ8(w[i], ss);
;             const float rn = rsqrtf(ss * rq * rq * (1.f / 96.f) + EPS) * rq;
;             u32x4* o = (u32x4*)(Qb + (bh * KVLEN + pos) * 96);
; #pragma unroll
;             for (int i = 0; i < 8; ++i) { UNPK(w[i], e); const float sc = rn * C2; u32x4 ow;
;                 ow.x = cvtpk(e[0] * sc * gqn[8 * i], e[1] * sc * gqn[8 * i + 1]); ow.y = cvtpk(e[2] * sc * gqn[8 * i + 2], e[3] * sc * gqn[8 * i + 3]);
	v_and_b32_e32 v110, 0xffff0000, v76
	v_pk_fma_f32 v[32:33], v[32:33], v[32:33], v[44:45]
	v_mov_b32_e32 v44, v66
	v_mov_b32_e32 v45, v72
	v_pk_mul_f32 v[62:63], v[62:63], v[62:63]
	v_mul_f32_e32 v81, 0x45800000, v80
	v_lshlrev_b32_e32 v123, 16, v77
	v_lshlrev_b32_e32 v122, 16, v76
	v_pk_mul_f32 v[76:77], v[110:111], v[110:111]
	v_and_b32_e32 v107, 0xffff0000, v79
	v_and_b32_e32 v106, 0xffff0000, v78
	v_pk_add_f32 v[32:33], v[32:33], v[32:33] op_sel:[0,1] op_sel_hi:[1,0]
	v_pk_fma_f32 v[44:45], v[44:45], v[44:45], v[62:63]
	v_pk_fma_f32 v[76:77], v[122:123], v[122:123], v[76:77]
	v_lshlrev_b32_e32 v135, 16, v79
	v_lshlrev_b32_e32 v134, 16, v78
	v_pk_mul_f32 v[78:79], v[106:107], v[106:107]
	v_cndmask_b32_e64 v119, v80, v81, s[8:9]
	v_pk_add_f32 v[32:33], v[44:45], v[32:33] op_sel:[1,0] op_sel_hi:[0,1]
	v_and_b32_e32 v81, 0xffff0000, v56
	v_pk_add_f32 v[76:77], v[76:77], v[76:77] op_sel:[0,1] op_sel_hi:[1,0]
	v_pk_fma_f32 v[78:79], v[134:135], v[134:135], v[78:79]
	v_pk_add_f32 v[142:143], v[44:45], v[32:33]
	v_lshlrev_b32_e32 v80, 16, v56
	v_mul_f32_e32 v32, v81, v81
	v_and_b32_e32 v83, 0xffff0000, v57
	v_pk_add_f32 v[76:77], v[78:79], v[76:77]
	v_pk_fma_f32 v[162:163], v[80:81], v[80:81], v[32:33] op_sel_hi:[1,1,0]
	v_cndmask_b32_e64 v32, 1.0, v10, s[6:7]
	v_lshlrev_b32_e32 v82, 16, v57
	v_mul_f32_e32 v10, v83, v83
	v_lshlrev_b32_e32 v94, 16, v58
	v_and_b32_e32 v95, 0xffff0000, v58
	v_lshlrev_b32_e32 v96, 16, v59
	v_and_b32_e32 v97, 0xffff0000, v59
	v_mov_b32_e32 v58, 0x180
	v_pk_add_f32 v[120:121], v[78:79], v[76:77] op_sel:[1,0] op_sel_hi:[0,1]
	v_lshlrev_b32_e32 v74, 16, v64
	v_and_b32_e32 v75, 0xffff0000, v64
	v_lshlrev_b32_e32 v78, 16, v65
	v_and_b32_e32 v79, 0xffff0000, v65
	v_lshlrev_b32_e32 v62, 16, v52
	v_and_b32_e32 v63, 0xffff0000, v52
	v_cndmask_b32_e64 v33, 1.0, v11, s[6:7]
	v_cndmask_b32_e64 v45, 0, v15, s[6:7]
	v_cndmask_b32_e64 v44, 0, v14, s[6:7]
	v_pk_fma_f32 v[164:165], v[82:83], v[82:83], v[10:11] op_sel_hi:[1,1,0]
	v_lshlrev_b32_e32 v64, 16, v53
	v_and_b32_e32 v65, 0xffff0000, v53
	v_cndmask_b32_e64 v53, 1.0, v1, s[6:7]
	v_cndmask_b32_e64 v52, 1.0, v0, s[6:7]
	v_cndmask_b32_e64 v57, 0, v5, s[6:7]
	v_cndmask_b32_e64 v56, 0, v4, s[6:7]
	v_cndmask_b32_e64 v11, 1.0, v3, s[6:7]
	v_cndmask_b32_e64 v10, 1.0, v2, s[6:7]
	v_cndmask_b32_e64 v15, 0, v7, s[6:7]
	v_cndmask_b32_e64 v14, 0, v6, s[6:7]
	ds_read_b128 v[0:3], v58 offset:16
	ds_read_b128 v[4:7], v58
	v_pk_mul_f32 v[156:157], v[78:79], v[78:79]
	v_and_b32_e32 v151, 0xffff0000, v51
	v_lshlrev_b32_e32 v152, 16, v50
	v_and_b32_e32 v153, 0xffff0000, v50
	v_lshlrev_b32_e32 v154, 16, v49
	v_and_b32_e32 v155, 0xffff0000, v49
	v_lshlrev_b32_e32 v158, 16, v48
	v_and_b32_e32 v159, 0xffff0000, v48
	v_and_b32_e32 v49, 0xffff0000, v36
	v_and_b32_e32 v48, 0xffff0000, v46
	v_pk_mov_b32 v[50:51], v[46:47], v[38:39] op_sel:[1,0]
	v_mov_b32_e32 v145, v156
	v_mov_b32_e32 v149, v157
	v_pk_mul_f32 v[166:167], v[64:65], v[64:65]
	v_lshlrev_b32_e32 v177, 16, v36
	v_lshlrev_b32_e32 v176, 16, v46
	v_lshlrev_b32_e32 v178, 16, v47
	v_and_b32_e32 v47, 0xffff0000, v51
	v_and_b32_e32 v46, 0xffff0000, v50
	v_pk_mul_f32 v[50:51], v[48:49], v[48:49]
	v_pk_add_f32 v[184:185], v[144:145], v[148:149]
	v_mov_b32_e32 v148, v95
	v_mov_b32_e32 v149, v63
	v_and_b32_e32 v77, 0xffff0000, v54
	v_lshlrev_b32_e32 v179, 16, v38
	v_pk_fma_f32 v[180:181], v[176:177], v[176:177], v[50:51]
	v_pk_mul_f32 v[50:51], v[46:47], v[46:47]
	v_mov_b32_e32 v163, v166
	v_mov_b32_e32 v165, v167
	v_mov_b32_e32 v144, v94
	v_mov_b32_e32 v145, v62
	v_pk_mul_f32 v[148:149], v[148:149], v[148:149]
	v_lshlrev_b32_e32 v76, 16, v54
	v_pk_fma_f32 v[182:183], v[178:179], v[178:179], v[50:51]
	v_pk_add_f32 v[50:51], v[162:163], v[164:165]
	v_pk_fma_f32 v[144:145], v[144:145], v[144:145], v[148:149]
	v_mov_b32_e32 v148, v97
	v_mov_b32_e32 v149, v77
	v_pk_add_f32 v[50:51], v[144:145], v[50:51]
	v_mov_b32_e32 v144, v96
	v_mov_b32_e32 v145, v76
	v_pk_mul_f32 v[148:149], v[148:149], v[148:149]
	v_and_b32_e32 v165, 0xffff0000, v42
	v_pk_fma_f32 v[144:145], v[144:145], v[144:145], v[148:149]
	v_and_b32_e32 v149, 0xffff0000, v43
	v_pk_add_f32 v[186:187], v[144:145], v[50:51]
	v_lshlrev_b32_e32 v148, 16, v43
	v_mov_b32_e32 v144, v151
	v_mov_b32_e32 v145, v149
	v_mov_b32_e32 v50, v150
	v_mov_b32_e32 v51, v148
	v_pk_mul_f32 v[144:145], v[144:145], v[144:145]
	v_lshlrev_b32_e32 v164, 16, v42
	v_pk_fma_f32 v[50:51], v[50:51], v[50:51], v[144:145]
	v_mov_b32_e32 v144, v153
	v_mov_b32_e32 v145, v165
	v_and_b32_e32 v167, 0xffff0000, v41
	v_mov_b32_e32 v42, v152
	v_mov_b32_e32 v43, v164
	v_pk_mul_f32 v[144:145], v[144:145], v[144:145]
	v_lshlrev_b32_e32 v166, 16, v41
	v_mov_b32_e32 v156, v155
	v_mov_b32_e32 v157, v167
	v_pk_fma_f32 v[42:43], v[42:43], v[42:43], v[144:145]
	v_mov_b32_e32 v144, v154
	v_mov_b32_e32 v145, v166
	v_pk_mul_f32 v[156:157], v[156:157], v[156:157]
	v_lshlrev_b32_e32 v192, 16, v40
	v_pk_fma_f32 v[144:145], v[144:145], v[144:145], v[156:157]
	v_mov_b32_e32 v156, v159
	v_mov_b32_e32 v157, v193
	v_mov_b32_e32 v40, v158
	v_mov_b32_e32 v41, v192
	v_pk_mul_f32 v[156:157], v[156:157], v[156:157]
	v_pk_mul_f32 v[146:147], v[90:91], v[90:91]
	v_pk_fma_f32 v[40:41], v[40:41], v[40:41], v[156:157]
	v_mov_b32_e32 v137, v147
	v_pk_add_f32 v[40:41], v[40:41], v[144:145]
	v_lshlrev_b32_e32 v54, 16, v55
	v_pk_add_f32 v[40:41], v[42:43], v[40:41]
	v_and_b32_e32 v55, 0xffff0000, v55
	v_pk_add_f32 v[40:41], v[50:51], v[40:41]
	v_lshlrev_b32_e32 v50, 16, v39
	v_pk_add_f32 v[40:41], v[40:41], v[40:41] op_sel:[0,1] op_sel_hi:[1,0]
	v_and_b32_e32 v51, 0xffff0000, v39
	v_pk_mul_f32 v[38:39], v[50:51], v[50:51]
	v_pk_add_f32 v[40:41], v[40:41], v[120:121]
; DI unsigned cvtpk(float lo, float hi) { f32x2_t v = {lo, hi}; bf16x2_t b = __builtin_convertvector(v, bf16x2_t); return __builtin_bit_cast(unsigned, b); }
; #define UNPK(W_, E_) const float E_[8] = {bflo((W_).x), bfhi((W_).x), bflo((W_).y), bfhi((W_).y), bflo((W_).z), bfhi((W_).z), bflo((W_).w), bfhi((W_).w)}
; DI void phase_mla_fin(ArgsP a, int tb_, int l, char* shm, int vcu, int G) {
;     ...
;             const float rn = rsqrtf(ss * rq * rq * (1.f / 96.f) + EPS) * rq;
;             u32x4* o = (u32x4*)(Qb + (bh * KVLEN + pos) * 96);
; #pragma unroll
;             for (int i = 0; i < 8; ++i) { UNPK(w[i], e); const float sc = rn * C2; u32x4 ow;
;                 ow.x = cvtpk(e[0] * sc * gqn[8 * i], e[1] * sc * gqn[8 * i + 1]); ow.y = cvtpk(e[2] * sc * gqn[8 * i + 2], e[3] * sc * gqn[8 * i + 3]);
;                 ow.z = cvtpk(e[4] * sc * gqn[8 * i + 4], e[5] * sc * gqn[8 * i + 5]); ow.w = cvtpk(e[6] * sc * gqn[8 * i + 6], e[7] * sc * gqn[8 * i + 7]); o[i] = ow; }
	v_mov_b32_e32 v131, v39
	v_mov_b32_e32 v41, v38
	v_pk_add_f32 v[38:39], v[40:41], v[130:131]
	v_lshlrev_b32_e32 v130, 16, v37
	v_and_b32_e32 v131, 0xffff0000, v37
	v_pk_mul_f32 v[36:37], v[130:131], v[130:131]
	v_mov_b32_e32 v120, v124
	v_mov_b32_e32 v127, v36
	v_mov_b32_e32 v133, v37
	v_pk_add_f32 v[36:37], v[126:127], v[132:133]
	v_mov_b32_e32 v121, v98
	v_pk_add_f32 v[36:37], v[180:181], v[36:37]
	v_mov_b32_e32 v98, v125
	v_pk_add_f32 v[36:37], v[182:183], v[36:37]
	v_mov_b32_e32 v125, v89
	v_pk_add_f32 v[36:37], v[38:39], v[36:37]
	v_mov_b32_e32 v41, v88
	v_pk_add_f32 v[36:37], v[36:37], v[36:37] op_sel:[0,1] op_sel_hi:[1,0]
	v_mov_b32_e32 v127, v75
	v_mov_b32_e32 v37, v146
	v_pk_add_f32 v[38:39], v[36:37], v[136:137]
	v_and_b32_e32 v37, 0xffff0000, v35
	v_lshlrev_b32_e32 v36, 16, v35
	v_mov_b32_e32 v124, v37
	v_mov_b32_e32 v40, v36
	v_pk_mul_f32 v[124:125], v[124:125], v[124:125]
	v_mov_b32_e32 v35, v74
	v_pk_fma_f32 v[124:125], v[40:41], v[40:41], v[124:125]
	v_and_b32_e32 v41, 0xffff0000, v34
	v_lshlrev_b32_e32 v40, 16, v34
	v_mov_b32_e32 v126, v41
	v_mov_b32_e32 v34, v40
	v_pk_mul_f32 v[126:127], v[126:127], v[126:127]
	v_pk_mul_f32 v[160:161], v[54:55], v[54:55]
	v_pk_fma_f32 v[34:35], v[34:35], v[34:35], v[126:127]
	v_mov_b32_e32 v143, v161
	v_pk_add_f32 v[34:35], v[34:35], v[184:185]
	v_mov_b32_e32 v162, v122
	v_pk_add_f32 v[34:35], v[124:125], v[34:35]
	v_mov_b32_e32 v163, v110
	v_pk_add_f32 v[34:35], v[38:39], v[34:35]
	v_mov_b32_e32 v110, v123
	v_pk_add_f32 v[34:35], v[34:35], v[34:35] op_sel:[0,1] op_sel_hi:[1,0]
	v_mov_b32_e32 v156, v134
	v_mov_b32_e32 v35, v160
	v_pk_add_f32 v[34:35], v[34:35], v[142:143]
	v_mov_b32_e32 v157, v106
	v_pk_add_f32 v[34:35], v[34:35], v[186:187]
	v_mov_b32_e32 v106, v135
	v_add_f32_e32 v34, v34, v35
	v_mul_f32_e32 v34, v34, v119
	v_mul_f32_e32 v34, v119, v34
	v_fmamk_f32 v34, v34, 0x3c2aaaab, v230
	v_cmp_gt_f32_e64 s[6:7], s76, v34
	v_mul_f32_e32 v35, 0x4b800000, v34
	v_mov_b32_e32 v144, v138
	v_cndmask_b32_e64 v34, v34, v35, s[6:7]
	v_rsq_f32_e32 v34, v34
	v_mov_b32_e32 v145, v108
	v_mov_b32_e32 v108, v139
	v_mov_b32_e32 v138, v140
	v_mul_f32_e32 v35, 0x45800000, v34
	v_cndmask_b32_e64 v34, v34, v35, s[6:7]
	v_mul_f32_e32 v34, v119, v34
	v_mul_f32_e32 v38, 0x3e16c740, v34
	v_pk_mul_f32 v[124:125], v[38:39], v[158:159] op_sel_hi:[0,1]
	s_waitcnt lgkmcnt(0)
	v_pk_mul_f32 v[4:5], v[4:5], v[124:125]
	v_pk_mul_f32 v[124:125], v[38:39], v[154:155] op_sel_hi:[0,1]
	v_pk_mul_f32 v[6:7], v[6:7], v[124:125]
	v_cvt_pk_bf16_f32 v4, v4, v5
	v_cvt_pk_bf16_f32 v5, v6, v7
	v_pk_mul_f32 v[6:7], v[38:39], v[152:153] op_sel_hi:[0,1]
	v_pk_mul_f32 v[0:1], v[0:1], v[6:7]
	v_mov_b32_e32 v139, v102
	v_cvt_pk_bf16_f32 v6, v0, v1
	v_pk_mul_f32 v[0:1], v[38:39], v[150:151] op_sel_hi:[0,1]
	v_pk_mul_f32 v[0:1], v[2:3], v[0:1]
	v_mov_b32_e32 v102, v141
	v_cvt_pk_bf16_f32 v7, v0, v1
	global_store_dwordx4 v[68:69], v[4:7], off
	s_nop 1
	ds_read_b128 v[0:3], v58 offset:32
	v_mov_b32_e32 v134, v176
	v_pk_mul_f32 v[4:5], v[38:39], v[192:193] op_sel_hi:[0,1]
	v_pk_mul_f32 v[6:7], v[38:39], v[164:165] op_sel_hi:[0,1]
	v_mov_b32_e32 v135, v48
	v_mov_b32_e32 v122, v178
	v_mov_b32_e32 v123, v46
	v_mov_b32_e32 v48, v177
	v_mov_b32_e32 v46, v179
	v_mov_b32_e32 v42, v128
	v_mov_b32_e32 v43, v92
	v_mov_b32_e32 v92, v129
	s_mov_b32 s0, 0x3e16c740
	s_waitcnt lgkmcnt(0)
	v_pk_mul_f32 v[0:1], v[0:1], v[4:5]
	v_pk_mul_f32 v[4:5], v[38:39], v[166:167] op_sel_hi:[0,1]
	v_pk_mul_f32 v[2:3], v[2:3], v[4:5]
	v_cvt_pk_bf16_f32 v0, v0, v1
	v_cvt_pk_bf16_f32 v1, v2, v3
	ds_read_b128 v[2:5], v58 offset:48
	s_waitcnt lgkmcnt(0)
	v_pk_mul_f32 v[2:3], v[2:3], v[6:7]
	v_pk_mul_f32 v[6:7], v[38:39], v[148:149] op_sel_hi:[0,1]
	v_pk_mul_f32 v[4:5], v[4:5], v[6:7]
	v_cvt_pk_bf16_f32 v2, v2, v3
	v_cvt_pk_bf16_f32 v3, v4, v5
	global_store_dwordx4 v[68:69], v[0:3], off offset:16
	s_nop 1
	ds_read_b128 v[0:3], v58 offset:64
	v_pk_mul_f32 v[4:5], v[38:39], v[162:163] op_sel_hi:[0,1]
	v_pk_mul_f32 v[6:7], v[38:39], v[156:157] op_sel_hi:[0,1]
	s_waitcnt lgkmcnt(0)
	v_pk_mul_f32 v[0:1], v[0:1], v[4:5]
	v_pk_mul_f32 v[4:5], v[38:39], v[110:111] op_sel_hi:[0,1]
	v_pk_mul_f32 v[2:3], v[2:3], v[4:5]
	v_cvt_pk_bf16_f32 v0, v0, v1
	v_cvt_pk_bf16_f32 v1, v2, v3
	ds_read_b128 v[2:5], v58 offset:80
	s_waitcnt lgkmcnt(0)
	v_pk_mul_f32 v[2:3], v[6:7], v[2:3]
	v_pk_mul_f32 v[6:7], v[38:39], v[106:107] op_sel_hi:[0,1]
	v_pk_mul_f32 v[4:5], v[6:7], v[4:5]
	v_cvt_pk_bf16_f32 v2, v2, v3
	v_cvt_pk_bf16_f32 v3, v4, v5
	global_store_dwordx4 v[68:69], v[0:3], off offset:32
	s_nop 1
	ds_read_b128 v[0:3], v58 offset:96
	v_pk_mul_f32 v[4:5], v[38:39], v[144:145] op_sel_hi:[0,1]
	v_pk_mul_f32 v[6:7], v[38:39], v[138:139] op_sel_hi:[0,1]
	s_waitcnt lgkmcnt(0)
	v_pk_mul_f32 v[0:1], v[4:5], v[0:1]
	v_pk_mul_f32 v[4:5], v[38:39], v[108:109] op_sel_hi:[0,1]
	v_pk_mul_f32 v[2:3], v[4:5], v[2:3]
	v_cvt_pk_bf16_f32 v0, v0, v1
	v_cvt_pk_bf16_f32 v1, v2, v3
	ds_read_b128 v[2:5], v58 offset:112
	s_waitcnt lgkmcnt(0)
	v_pk_mul_f32 v[2:3], v[6:7], v[2:3]
	v_pk_mul_f32 v[6:7], v[38:39], v[102:103] op_sel_hi:[0,1]
	v_pk_mul_f32 v[4:5], v[6:7], v[4:5]
	v_cvt_pk_bf16_f32 v2, v2, v3
	v_cvt_pk_bf16_f32 v3, v4, v5
	global_store_dwordx4 v[68:69], v[0:3], off offset:48
	s_nop 1
	ds_read_b128 v[0:3], v58 offset:128
	v_pk_mul_f32 v[4:5], v[38:39], v[104:105] op_sel_hi:[0,1]
	v_pk_mul_f32 v[6:7], v[38:39], v[134:135] op_sel_hi:[0,1]
	s_waitcnt lgkmcnt(0)
	v_pk_mul_f32 v[0:1], v[4:5], v[0:1]
	v_pk_mul_f32 v[4:5], v[38:39], v[100:101] op_sel_hi:[0,1]
	v_pk_mul_f32 v[2:3], v[4:5], v[2:3]
	v_cvt_pk_bf16_f32 v0, v0, v1
	v_cvt_pk_bf16_f32 v1, v2, v3
	ds_read_b128 v[2:5], v58 offset:144
	s_waitcnt lgkmcnt(0)
; DI unsigned cvtpk(float lo, float hi) { f32x2_t v = {lo, hi}; bf16x2_t b = __builtin_convertvector(v, bf16x2_t); return __builtin_bit_cast(unsigned, b); }
; #define UNPK(W_, E_) const float E_[8] = {bflo((W_).x), bfhi((W_).x), bflo((W_).y), bfhi((W_).y), bflo((W_).z), bfhi((W_).z), bflo((W_).w), bfhi((W_).w)}
; #define ROPE32(xr) _Pragma("unroll") for (int ax = 0; ax < 2; ++ax) _Pragma("unroll") for (int f = 0; f < 8; ++f) { const float x1 = xr[16 * ax + f], x2 = xr[16 * ax + 8 + f], c = cs[8 * ax + f], sv = sn[8 * ax + f]; xr[16 * ax + f] = x1 * c - x2 * sv; xr[16 * ax + 8 + f] = x2 * c + x1 * sv; }
; DI void phase_mla_fin(ArgsP a, int tb_, int l, char* shm, int vcu, int G) {
;     ...
;             for (int i = 0; i < 8; ++i) { UNPK(w[i], e); const float sc = rn * C2; u32x4 ow;
;                 ow.x = cvtpk(e[0] * sc * gqn[8 * i], e[1] * sc * gqn[8 * i + 1]); ow.y = cvtpk(e[2] * sc * gqn[8 * i + 2], e[3] * sc * gqn[8 * i + 3]);
;                 ow.z = cvtpk(e[4] * sc * gqn[8 * i + 4], e[5] * sc * gqn[8 * i + 5]); ow.w = cvtpk(e[6] * sc * gqn[8 * i + 6], e[7] * sc * gqn[8 * i + 7]); o[i] = ow; }
;             float xr[32];
; #pragma unroll
;             for (int i = 0; i < 4; ++i) { UNPK(w[8 + i], e);
; #pragma unroll
;                 for (int j = 0; j < 8; ++j) xr[8 * i + j] = e[j] * rn * C2 * gqn[64 + 8 * i + j]; }
;             ROPE32(xr)
; #pragma unroll
;             for (int i = 0; i < 4; ++i) { u32x4 ow; ow.x = cvtpk(xr[8 * i], xr[8 * i + 1]); ow.y = cvtpk(xr[8 * i + 2], xr[8 * i + 3]); ow.z = cvtpk(xr[8 * i + 4], xr[8 * i + 5]); ow.w = cvtpk(xr[8 * i + 6], xr[8 * i + 7]); o[8 + i] = ow; }
	v_pk_mul_f32 v[2:3], v[6:7], v[2:3]
	v_pk_mul_f32 v[6:7], v[38:39], v[122:123] op_sel_hi:[0,1]
	v_pk_mul_f32 v[4:5], v[6:7], v[4:5]
	v_cvt_pk_bf16_f32 v2, v2, v3
	v_cvt_pk_bf16_f32 v3, v4, v5
	global_store_dwordx4 v[68:69], v[0:3], off offset:64
	s_nop 1
	ds_read_b128 v[0:3], v58 offset:160
	v_pk_mul_f32 v[4:5], v[38:39], v[48:49] op_sel_hi:[0,1]
	v_pk_mul_f32 v[6:7], v[38:39], v[46:47] op_sel_hi:[0,1]
	s_waitcnt lgkmcnt(0)
	v_pk_mul_f32 v[0:1], v[4:5], v[0:1]
	v_pk_mul_f32 v[4:5], v[38:39], v[130:131] op_sel_hi:[0,1]
	v_pk_mul_f32 v[2:3], v[4:5], v[2:3]
	v_cvt_pk_bf16_f32 v0, v0, v1
	v_cvt_pk_bf16_f32 v1, v2, v3
	ds_read_b128 v[2:5], v58 offset:176
	s_waitcnt lgkmcnt(0)
	v_pk_mul_f32 v[2:3], v[6:7], v[2:3]
	v_pk_mul_f32 v[6:7], v[38:39], v[50:51] op_sel_hi:[0,1]
	v_pk_mul_f32 v[4:5], v[6:7], v[4:5]
	v_cvt_pk_bf16_f32 v2, v2, v3
	v_cvt_pk_bf16_f32 v3, v4, v5
	global_store_dwordx4 v[68:69], v[0:3], off offset:80
	s_nop 1
	ds_read_b128 v[0:3], v58 offset:192
	v_pk_mul_f32 v[4:5], v[38:39], v[120:121] op_sel_hi:[0,1]
	v_pk_mul_f32 v[6:7], v[38:39], v[42:43] op_sel_hi:[0,1]
	s_waitcnt lgkmcnt(0)
	v_pk_mul_f32 v[0:1], v[4:5], v[0:1]
	v_pk_mul_f32 v[4:5], v[38:39], v[98:99] op_sel_hi:[0,1]
	v_pk_mul_f32 v[2:3], v[4:5], v[2:3]
	v_cvt_pk_bf16_f32 v0, v0, v1
	v_cvt_pk_bf16_f32 v1, v2, v3
	ds_read_b128 v[2:5], v58 offset:208
	s_waitcnt lgkmcnt(0)
	v_pk_mul_f32 v[2:3], v[6:7], v[2:3]
	v_pk_mul_f32 v[6:7], v[38:39], v[92:93] op_sel_hi:[0,1]
	v_pk_mul_f32 v[4:5], v[6:7], v[4:5]
	v_cvt_pk_bf16_f32 v2, v2, v3
	v_cvt_pk_bf16_f32 v3, v4, v5
	global_store_dwordx4 v[68:69], v[0:3], off offset:96
	s_nop 1
	ds_read_b128 v[0:3], v58 offset:224
	v_pk_mul_f32 v[4:5], v[38:39], v[86:87] op_sel_hi:[0,1]
	v_pk_mul_f32 v[6:7], v[38:39], v[40:41] op_sel_hi:[0,1]
	s_waitcnt lgkmcnt(0)
	v_pk_mul_f32 v[0:1], v[4:5], v[0:1]
	v_pk_mul_f32 v[4:5], v[38:39], v[84:85] op_sel_hi:[0,1]
	v_pk_mul_f32 v[2:3], v[4:5], v[2:3]
	v_cvt_pk_bf16_f32 v0, v0, v1
	v_cvt_pk_bf16_f32 v1, v2, v3
	ds_read_b128 v[2:5], v58 offset:240
	s_waitcnt lgkmcnt(0)
	v_pk_mul_f32 v[2:3], v[6:7], v[2:3]
	v_pk_mul_f32 v[6:7], v[38:39], v[36:37] op_sel_hi:[0,1]
	v_pk_mul_f32 v[4:5], v[6:7], v[4:5]
	v_cvt_pk_bf16_f32 v2, v2, v3
	v_cvt_pk_bf16_f32 v3, v4, v5
	global_store_dwordx4 v[68:69], v[0:3], off offset:112
	s_nop 1
	v_pk_mul_f32 v[0:1], v[34:35], v[74:75] op_sel_hi:[0,1]
	v_pk_mul_f32 v[4:5], v[0:1], s[0:1] op_sel_hi:[1,0]
	ds_read_b128 v[0:3], v58 offset:256
	s_waitcnt lgkmcnt(0)
	v_pk_mul_f32 v[6:7], v[4:5], v[0:1]
	v_pk_mul_f32 v[0:1], v[34:35], v[78:79] op_sel_hi:[0,1]
	v_pk_mul_f32 v[0:1], v[0:1], s[0:1] op_sel_hi:[1,0]
	s_nop 0
	v_pk_mul_f32 v[4:5], v[0:1], v[2:3]
	v_pk_mul_f32 v[0:1], v[34:35], v[88:89] op_sel_hi:[0,1]
	v_pk_mul_f32 v[36:37], v[0:1], s[0:1] op_sel_hi:[1,0]
	ds_read_b128 v[0:3], v58 offset:272
	s_waitcnt lgkmcnt(0)
	v_pk_mul_f32 v[38:39], v[36:37], v[0:1]
	v_pk_mul_f32 v[0:1], v[34:35], v[90:91] op_sel_hi:[0,1]
	v_pk_mul_f32 v[0:1], v[0:1], s[0:1] op_sel_hi:[1,0]
	s_nop 0
	v_pk_mul_f32 v[36:37], v[0:1], v[2:3]
	v_pk_mul_f32 v[0:1], v[34:35], v[70:71] op_sel_hi:[0,1]
	v_pk_mul_f32 v[40:41], v[0:1], s[0:1] op_sel_hi:[1,0]
	ds_read_b128 v[0:3], v58 offset:288
	s_waitcnt lgkmcnt(0)
	v_pk_mul_f32 v[46:47], v[40:41], v[0:1]
	v_pk_mul_f32 v[0:1], v[34:35], v[60:61] op_sel_hi:[0,1]
	v_pk_mul_f32 v[0:1], v[0:1], s[0:1] op_sel_hi:[1,0]
	s_nop 0
	v_pk_mul_f32 v[42:43], v[0:1], v[2:3]
	v_pk_mul_f32 v[0:1], v[34:35], v[72:73] op_sel_hi:[0,1]
	v_pk_mul_f32 v[40:41], v[0:1], s[0:1] op_sel_hi:[1,0]
	ds_read_b128 v[0:3], v58 offset:304
	s_waitcnt lgkmcnt(0)
	v_pk_mul_f32 v[60:61], v[40:41], v[0:1]
	v_pk_mul_f32 v[0:1], v[34:35], v[66:67] op_sel_hi:[0,1]
	v_pk_mul_f32 v[0:1], v[0:1], s[0:1] op_sel_hi:[1,0]
	s_nop 0
	v_pk_mul_f32 v[48:49], v[0:1], v[2:3]
	v_pk_mul_f32 v[0:1], v[34:35], v[80:81] op_sel_hi:[0,1]
	v_pk_mul_f32 v[40:41], v[0:1], s[0:1] op_sel_hi:[1,0]
	ds_read_b128 v[0:3], v58 offset:320
	s_waitcnt lgkmcnt(0)
	v_pk_mul_f32 v[66:67], v[40:41], v[0:1]
	v_pk_mul_f32 v[0:1], v[34:35], v[82:83] op_sel_hi:[0,1]
	v_pk_mul_f32 v[0:1], v[0:1], s[0:1] op_sel_hi:[1,0]
	s_nop 0
	v_pk_mul_f32 v[50:51], v[0:1], v[2:3]
	v_pk_mul_f32 v[0:1], v[34:35], v[94:95] op_sel_hi:[0,1]
	v_pk_mul_f32 v[40:41], v[0:1], s[0:1] op_sel_hi:[1,0]
	ds_read_b128 v[0:3], v58 offset:336
	s_waitcnt lgkmcnt(0)
	v_pk_mul_f32 v[70:71], v[40:41], v[0:1]
	v_pk_mul_f32 v[0:1], v[34:35], v[96:97] op_sel_hi:[0,1]
	v_pk_mul_f32 v[0:1], v[0:1], s[0:1] op_sel_hi:[1,0]
	s_nop 0
	v_pk_mul_f32 v[40:41], v[0:1], v[2:3]
	v_pk_mul_f32 v[0:1], v[34:35], v[62:63] op_sel_hi:[0,1]
	v_pk_mul_f32 v[62:63], v[0:1], s[0:1] op_sel_hi:[1,0]
	ds_read_b128 v[0:3], v58 offset:352
	s_waitcnt lgkmcnt(0)
	v_pk_mul_f32 v[72:73], v[62:63], v[0:1]
	v_pk_mul_f32 v[0:1], v[34:35], v[64:65] op_sel_hi:[0,1]
	v_pk_mul_f32 v[0:1], v[0:1], s[0:1] op_sel_hi:[1,0]
	s_nop 0
	v_pk_mul_f32 v[62:63], v[0:1], v[2:3]
	v_pk_mul_f32 v[0:1], v[34:35], v[76:77] op_sel_hi:[0,1]
	v_pk_mul_f32 v[64:65], v[0:1], s[0:1] op_sel_hi:[1,0]
	ds_read_b128 v[0:3], v58 offset:368
	v_pk_mul_f32 v[34:35], v[34:35], v[54:55] op_sel_hi:[0,1]
	v_pk_mul_f32 v[34:35], v[34:35], s[0:1] op_sel_hi:[1,0]
	s_waitcnt lgkmcnt(0)
	v_pk_mul_f32 v[0:1], v[64:65], v[0:1]
	v_pk_mul_f32 v[2:3], v[34:35], v[2:3]
	v_pk_mul_f32 v[34:35], v[24:25], v[46:47]
	v_pk_mul_f32 v[46:47], v[28:29], v[46:47]
	v_pk_fma_f32 v[64:65], v[28:29], v[6:7], v[34:35]
	v_pk_fma_f32 v[58:59], v[24:25], v[6:7], v[46:47] neg_lo:[0,0,1] neg_hi:[0,0,1]
	v_pk_mul_f32 v[6:7], v[26:27], v[42:43]
	v_pk_mul_f32 v[24:25], v[30:31], v[42:43]
	v_pk_fma_f32 v[74:75], v[30:31], v[4:5], v[6:7]
	v_pk_fma_f32 v[34:35], v[26:27], v[4:5], v[24:25] neg_lo:[0,0,1] neg_hi:[0,0,1]
	v_pk_mul_f32 v[4:5], v[16:17], v[60:61]
	v_pk_mul_f32 v[6:7], v[20:21], v[60:61]
	v_pk_fma_f32 v[78:79], v[20:21], v[38:39], v[4:5]
	v_pk_fma_f32 v[76:77], v[16:17], v[38:39], v[6:7] neg_lo:[0,0,1] neg_hi:[0,0,1]
	v_pk_mul_f32 v[4:5], v[18:19], v[48:49]
	v_pk_mul_f32 v[6:7], v[22:23], v[48:49]
	v_pk_fma_f32 v[80:81], v[22:23], v[36:37], v[4:5]
	v_pk_fma_f32 v[38:39], v[18:19], v[36:37], v[6:7] neg_lo:[0,0,1] neg_hi:[0,0,1]
	v_pk_mul_f32 v[4:5], v[8:9], v[72:73]
	v_pk_mul_f32 v[6:7], v[12:13], v[72:73]
	s_nop 0
	v_pk_fma_f32 v[36:37], v[8:9], v[66:67], v[6:7] neg_lo:[0,0,1] neg_hi:[0,0,1]
	v_pk_fma_f32 v[66:67], v[12:13], v[66:67], v[4:5]
	v_pk_mul_f32 v[4:5], v[32:33], v[62:63]
	v_pk_mul_f32 v[6:7], v[44:45], v[62:63]
	v_pk_fma_f32 v[42:43], v[44:45], v[50:51], v[4:5]
	v_pk_mul_f32 v[4:5], v[52:53], v[0:1]
	v_pk_mul_f32 v[0:1], v[56:57], v[0:1]
	v_pk_fma_f32 v[32:33], v[32:33], v[50:51], v[6:7] neg_lo:[0,0,1] neg_hi:[0,0,1]
	v_pk_fma_f32 v[44:45], v[52:53], v[70:71], v[0:1] neg_lo:[0,0,1] neg_hi:[0,0,1]
	v_pk_mul_f32 v[0:1], v[10:11], v[2:3]
	v_pk_mul_f32 v[2:3], v[14:15], v[2:3]
	v_pk_fma_f32 v[48:49], v[56:57], v[70:71], v[4:5]
	v_pk_fma_f32 v[50:51], v[10:11], v[40:41], v[2:3] neg_lo:[0,0,1] neg_hi:[0,0,1]
	v_pk_fma_f32 v[40:41], v[14:15], v[40:41], v[0:1]
	s_branch .LBB0_964
